# sigmoid epilogues: IEEE div sequence -> v_rcp_f32 (f32), dead helper chains removed
# speedup vs baseline: 1.0317x; 1.0317x over previous
; DI unsigned pk2(float lo, float hi) { f32x2_t v = {lo, hi}; bf16x2_t b = __builtin_convertvector(v, bf16x2_t); return __builtin_bit_cast(unsigned, b); }
; DI float sigmoidf_(float x) { return 1.0f / (1.0f + __expf(-x)); }
;     DI void operator()(AccRef acc, const Unit& u, int wr, int wc, int fr, int fq) const {
;     ...
;                 const int row = row0 + ai * HALF + m * 16; const float rs = rsqrtf(SS0[row] * (1.0f / DM) + EPSN);
; #pragma unroll
;                 for (int bj = 0; bj < 2; ++bj) {
;                     const f32x4 v0 = acc[ai][bj][m][0] * rs, v1 = acc[ai][bj][m][1] * rs;
;                     u32x4 w; w.x = pk2(sigmoidf_(v0[0]), sigmoidf_(v0[1])); w.y = pk2(sigmoidf_(v0[2]), sigmoidf_(v0[3])); w.z = pk2(sigmoidf_(v1[0]), sigmoidf_(v1[1])); w.w = pk2(sigmoidf_(v1[2]), sigmoidf_(v1[3]));
;                     *(u32x4*)(D + (size_t)row * DM + col0 + bj * HALF) = w;
.LBB0_1250:
	v_lshl_add_u32 v146, s0, 8, v160
	v_ashrrev_i32_e32 v147, 31, v146
	v_lshl_add_u64 v[144:145], v[146:147], 2, s[82:83]
	global_load_dword v152, v[144:145], off
	v_lshlrev_b64 v[174:175], 11, v[146:147]
	s_waitcnt vmcnt(0)
	v_fmamk_f32 v152, v152, 0x3a800000, v172
	v_mul_f32_e32 v154, 0x4b800000, v152
	v_cmp_gt_f32_e32 vcc, s62, v152
	s_nop 1
	v_cndmask_b32_e32 v152, v152, v154, vcc
	v_rsq_f32_e32 v152, v152
	v_lshl_or_b32 v154, s1, 8, v162
	v_ashrrev_i32_e32 v155, 31, v154
	v_mul_f32_e32 v147, 0x45800000, v152
	v_cndmask_b32_e32 v152, v152, v147, vcc
	v_pk_mul_f32 v[124:125], v[124:125], v[152:153] op_sel_hi:[1,0]
	v_pk_mul_f32 v[126:127], v[126:127], v[152:153] op_sel_hi:[1,0]
	v_pk_mul_f32 v[120:121], v[120:121], v[152:153] op_sel_hi:[1,0]
	v_mul_f32_e32 v124, 0xbfb8aa3b, v124
	v_mul_f32_e32 v125, 0xbfb8aa3b, v125
	v_pk_mul_f32 v[122:123], v[122:123], v[152:153] op_sel_hi:[1,0]
	v_mul_f32_e32 v126, 0xbfb8aa3b, v126
	v_mul_f32_e32 v127, 0xbfb8aa3b, v127
	v_mul_f32_e32 v147, 0xbfb8aa3b, v120
	v_mul_f32_e32 v173, 0xbfb8aa3b, v121
	v_exp_f32_e32 v120, v124
	v_exp_f32_e32 v121, v125
	v_mul_f32_e32 v176, 0xbfb8aa3b, v122
	v_mul_f32_e32 v178, 0xbfb8aa3b, v123
	v_exp_f32_e32 v122, v126
	v_exp_f32_e32 v123, v127
	v_exp_f32_e32 v124, v147
	v_exp_f32_e32 v125, v173
	v_pk_add_f32 v[120:121], v[120:121], 1.0 op_sel_hi:[1,0]
	v_exp_f32_e32 v126, v176
	v_pk_add_f32 v[176:177], v[122:123], 1.0 op_sel_hi:[1,0]
	v_pk_add_f32 v[124:125], v[124:125], 1.0 op_sel_hi:[1,0]
	v_rcp_f32_e32 v121, v121
	v_rcp_f32_e32 v120, v120
	s_nop 0
	v_cvt_pk_bf16_f32 v122, v120, v121
	v_rcp_f32_e32 v125, v125
	v_exp_f32_e32 v127, v178
	v_rcp_f32_e32 v120, v177
	v_rcp_f32_e32 v121, v176
	s_nop 0
	v_cvt_pk_bf16_f32 v123, v121, v120
	v_pk_add_f32 v[120:121], v[126:127], 1.0 op_sel_hi:[1,0]
	v_rcp_f32_e32 v124, v124
	s_nop 0
	v_cvt_pk_bf16_f32 v124, v124, v125
	v_rcp_f32_e32 v121, v121
	v_pk_mul_f32 v[116:117], v[116:117], v[152:153] op_sel_hi:[1,0]
	v_mul_f32_e32 v116, 0xbfb8aa3b, v116
	v_lshl_add_u64 v[126:127], s[54:55], 0, v[174:175]
	v_exp_f32_e32 v174, v116
	v_mul_f32_e32 v116, 0xbfb8aa3b, v117
	v_exp_f32_e32 v175, v116
	v_rcp_f32_e32 v120, v120
	s_nop 0
	v_cvt_pk_bf16_f32 v125, v120, v121
	v_lshlrev_b64 v[120:121], 1, v[154:155]
	v_lshl_add_u64 v[116:117], v[126:127], 0, v[120:121]
	global_store_dwordx4 v[116:117], v[122:125], off
	v_pk_mul_f32 v[118:119], v[118:119], v[152:153] op_sel_hi:[1,0]
	v_pk_mul_f32 v[114:115], v[114:115], v[152:153] op_sel_hi:[1,0]
	v_pk_add_f32 v[122:123], v[174:175], 1.0 op_sel_hi:[1,0]
	v_pk_mul_f32 v[124:125], v[112:113], v[152:153] op_sel_hi:[1,0]
	v_mul_f32_e32 v114, 0xbfb8aa3b, v114
	v_mul_f32_e32 v115, 0xbfb8aa3b, v115
	v_exp_f32_e32 v114, v114
	v_rcp_f32_e32 v123, v123
	v_mul_f32_e32 v113, 0xbfb8aa3b, v119
	v_mul_f32_e32 v112, 0xbfb8aa3b, v118
	v_exp_f32_e32 v112, v112
	v_exp_f32_e32 v113, v113
	s_nop 0
	v_pk_add_f32 v[118:119], v[112:113], 1.0 op_sel_hi:[1,0]
	v_rcp_f32_e32 v112, v122
	s_nop 0
	v_cvt_pk_bf16_f32 v112, v112, v123
	v_mul_f32_e32 v122, 0xbfb8aa3b, v124
	v_mul_f32_e32 v123, 0xbfb8aa3b, v125
	v_exp_f32_e32 v122, v122
	v_exp_f32_e32 v123, v123
	v_rcp_f32_e32 v113, v119
	v_pk_add_f32 v[122:123], v[122:123], 1.0 op_sel_hi:[1,0]
	v_rcp_f32_e32 v118, v118
	s_nop 0
	v_cvt_pk_bf16_f32 v113, v118, v113
	v_rcp_f32_e32 v123, v123
	v_exp_f32_e32 v115, v115
	s_nop 0
	v_pk_add_f32 v[118:119], v[114:115], 1.0 op_sel_hi:[1,0]
	v_rcp_f32_e32 v114, v122
	s_nop 0
	v_cvt_pk_bf16_f32 v114, v114, v123
	v_rcp_f32_e32 v115, v119
	v_rcp_f32_e32 v118, v118
	s_nop 0
	v_cvt_pk_bf16_f32 v115, v118, v115
	global_store_dwordx4 v[116:117], v[112:115], off offset:256
	global_load_dword v112, v[144:145], off offset:64
	s_nop 0
	v_or_b32_e32 v114, 16, v146
	v_ashrrev_i32_e32 v115, 31, v114
	v_lshlrev_b64 v[114:115], 11, v[114:115]
	s_waitcnt vmcnt(0)
	v_fmamk_f32 v112, v112, 0x3a800000, v172
	v_mul_f32_e32 v113, 0x4b800000, v112
	v_cmp_gt_f32_e32 vcc, s62, v112
	s_nop 1
	v_cndmask_b32_e32 v112, v112, v113, vcc
	v_rsq_f32_e32 v112, v112
	s_nop 0
	v_mul_f32_e32 v113, 0x45800000, v112
	v_cndmask_b32_e32 v112, v112, v113, vcc
	v_pk_mul_f32 v[108:109], v[108:109], v[112:113] op_sel_hi:[1,0]
	s_nop 0
	v_mul_f32_e32 v108, 0xbfb8aa3b, v108
	v_mul_f32_e32 v109, 0xbfb8aa3b, v109
	v_exp_f32_e32 v108, v108
	v_exp_f32_e32 v109, v109
	s_nop 0
	v_pk_add_f32 v[108:109], v[108:109], 1.0 op_sel_hi:[1,0]
	s_nop 0
	v_pk_mul_f32 v[118:119], v[104:105], v[112:113] op_sel_hi:[1,0]
	v_pk_mul_f32 v[110:111], v[110:111], v[112:113] op_sel_hi:[1,0]
	v_pk_mul_f32 v[106:107], v[106:107], v[112:113] op_sel_hi:[1,0]
	v_rcp_f32_e32 v109, v109
	v_mul_f32_e32 v105, 0xbfb8aa3b, v111
	v_mul_f32_e32 v104, 0xbfb8aa3b, v110
	v_exp_f32_e32 v104, v104
	v_exp_f32_e32 v105, v105
	s_nop 0
	v_pk_add_f32 v[110:111], v[104:105], 1.0 op_sel_hi:[1,0]
	v_rcp_f32_e32 v104, v108
	s_nop 0
	v_cvt_pk_bf16_f32 v104, v104, v109
	v_mul_f32_e32 v109, 0xbfb8aa3b, v119
	v_mul_f32_e32 v108, 0xbfb8aa3b, v118
	v_exp_f32_e32 v108, v108
	v_exp_f32_e32 v109, v109
	v_rcp_f32_e32 v105, v111
	v_pk_add_f32 v[108:109], v[108:109], 1.0 op_sel_hi:[1,0]
	v_rcp_f32_e32 v110, v110
	s_nop 0
	v_cvt_pk_bf16_f32 v105, v110, v105
	v_rcp_f32_e32 v109, v109
	v_mul_f32_e32 v106, 0xbfb8aa3b, v106
	v_mul_f32_e32 v107, 0xbfb8aa3b, v107
	v_exp_f32_e32 v106, v106
	v_exp_f32_e32 v107, v107
	s_nop 0
	v_pk_add_f32 v[110:111], v[106:107], 1.0 op_sel_hi:[1,0]
	v_rcp_f32_e32 v106, v108
	s_nop 0
	v_cvt_pk_bf16_f32 v106, v106, v109
	v_rcp_f32_e32 v107, v111
	v_pk_mul_f32 v[100:101], v[100:101], v[112:113] op_sel_hi:[1,0]
	v_mul_f32_e32 v100, 0xbfb8aa3b, v100
	v_mul_f32_e32 v101, 0xbfb8aa3b, v101
	v_exp_f32_e32 v100, v100
	v_exp_f32_e32 v101, v101
; DI unsigned pk2(float lo, float hi) { f32x2_t v = {lo, hi}; bf16x2_t b = __builtin_convertvector(v, bf16x2_t); return __builtin_bit_cast(unsigned, b); }
; DI float sigmoidf_(float x) { return 1.0f / (1.0f + __expf(-x)); }
;     DI void operator()(AccRef acc, const Unit& u, int wr, int wc, int fr, int fq) const {
;     ...
;                 const int row = row0 + ai * HALF + m * 16; const float rs = rsqrtf(SS0[row] * (1.0f / DM) + EPSN);
; #pragma unroll
;                 for (int bj = 0; bj < 2; ++bj) {
;                     const f32x4 v0 = acc[ai][bj][m][0] * rs, v1 = acc[ai][bj][m][1] * rs;
;                     u32x4 w; w.x = pk2(sigmoidf_(v0[0]), sigmoidf_(v0[1])); w.y = pk2(sigmoidf_(v0[2]), sigmoidf_(v0[3])); w.z = pk2(sigmoidf_(v1[0]), sigmoidf_(v1[1])); w.w = pk2(sigmoidf_(v1[2]), sigmoidf_(v1[3]));
;                     *(u32x4*)(D + (size_t)row * DM + col0 + bj * HALF) = w;
	v_rcp_f32_e32 v108, v110
	s_nop 0
	v_cvt_pk_bf16_f32 v107, v108, v107
	v_lshl_add_u64 v[108:109], s[54:55], 0, v[114:115]
	v_lshl_add_u64 v[108:109], v[108:109], 0, v[120:121]
	v_pk_add_f32 v[100:101], v[100:101], 1.0 op_sel_hi:[1,0]
	global_store_dwordx4 v[108:109], v[104:107], off
	v_pk_mul_f32 v[102:103], v[102:103], v[112:113] op_sel_hi:[1,0]
	v_pk_mul_f32 v[98:99], v[98:99], v[112:113] op_sel_hi:[1,0]
	v_pk_mul_f32 v[104:105], v[96:97], v[112:113] op_sel_hi:[1,0]
	v_mul_f32_e32 v98, 0xbfb8aa3b, v98
	v_mul_f32_e32 v99, 0xbfb8aa3b, v99
	v_rcp_f32_e32 v101, v101
	v_mul_f32_e32 v97, 0xbfb8aa3b, v103
	v_mul_f32_e32 v96, 0xbfb8aa3b, v102
	v_exp_f32_e32 v96, v96
	v_exp_f32_e32 v97, v97
	s_nop 0
	v_pk_add_f32 v[102:103], v[96:97], 1.0 op_sel_hi:[1,0]
	v_rcp_f32_e32 v96, v100
	s_nop 0
	v_cvt_pk_bf16_f32 v96, v96, v101
	v_mul_f32_e32 v101, 0xbfb8aa3b, v105
	v_mul_f32_e32 v100, 0xbfb8aa3b, v104
	v_exp_f32_e32 v100, v100
	v_exp_f32_e32 v101, v101
	v_rcp_f32_e32 v97, v103
	v_pk_add_f32 v[100:101], v[100:101], 1.0 op_sel_hi:[1,0]
	v_rcp_f32_e32 v102, v102
	s_nop 0
	v_cvt_pk_bf16_f32 v97, v102, v97
	v_rcp_f32_e32 v101, v101
	v_exp_f32_e32 v98, v98
	v_exp_f32_e32 v99, v99
	s_nop 0
	v_pk_add_f32 v[102:103], v[98:99], 1.0 op_sel_hi:[1,0]
	v_rcp_f32_e32 v98, v100
	s_nop 0
	v_cvt_pk_bf16_f32 v98, v98, v101
	v_rcp_f32_e32 v99, v103
	v_rcp_f32_e32 v100, v102
	s_nop 0
	v_cvt_pk_bf16_f32 v99, v100, v99
	global_store_dwordx4 v[108:109], v[96:99], off offset:256
	global_load_dword v96, v[144:145], off offset:128
	s_nop 0
	v_or_b32_e32 v98, 32, v146
	v_ashrrev_i32_e32 v99, 31, v98
	v_lshlrev_b64 v[98:99], 11, v[98:99]
	s_waitcnt vmcnt(0)
	v_fmamk_f32 v96, v96, 0x3a800000, v172
	v_mul_f32_e32 v97, 0x4b800000, v96
	v_cmp_gt_f32_e32 vcc, s62, v96
	s_nop 1
	v_cndmask_b32_e32 v96, v96, v97, vcc
	v_rsq_f32_e32 v96, v96
	s_nop 0
	v_mul_f32_e32 v97, 0x45800000, v96
	v_cndmask_b32_e32 v96, v96, v97, vcc
	v_pk_mul_f32 v[92:93], v[92:93], v[96:97] op_sel_hi:[1,0]
	s_nop 0
	v_mul_f32_e32 v92, 0xbfb8aa3b, v92
	v_mul_f32_e32 v93, 0xbfb8aa3b, v93
	v_exp_f32_e32 v92, v92
	v_exp_f32_e32 v93, v93
	s_nop 0
	v_pk_add_f32 v[92:93], v[92:93], 1.0 op_sel_hi:[1,0]
	s_nop 0
	v_pk_mul_f32 v[100:101], v[88:89], v[96:97] op_sel_hi:[1,0]
	v_pk_mul_f32 v[94:95], v[94:95], v[96:97] op_sel_hi:[1,0]
	v_pk_mul_f32 v[90:91], v[90:91], v[96:97] op_sel_hi:[1,0]
	v_rcp_f32_e32 v93, v93
	v_mul_f32_e32 v89, 0xbfb8aa3b, v95
	v_mul_f32_e32 v88, 0xbfb8aa3b, v94
	v_exp_f32_e32 v88, v88
	v_exp_f32_e32 v89, v89
	s_nop 0
	v_pk_add_f32 v[94:95], v[88:89], 1.0 op_sel_hi:[1,0]
	v_rcp_f32_e32 v88, v92
	s_nop 0
	v_cvt_pk_bf16_f32 v88, v88, v93
	v_mul_f32_e32 v93, 0xbfb8aa3b, v101
	v_mul_f32_e32 v92, 0xbfb8aa3b, v100
	v_exp_f32_e32 v92, v92
	v_exp_f32_e32 v93, v93
	v_rcp_f32_e32 v89, v95
	v_pk_add_f32 v[92:93], v[92:93], 1.0 op_sel_hi:[1,0]
	v_rcp_f32_e32 v94, v94
	s_nop 0
	v_cvt_pk_bf16_f32 v89, v94, v89
	v_rcp_f32_e32 v93, v93
	v_mul_f32_e32 v90, 0xbfb8aa3b, v90
	v_mul_f32_e32 v91, 0xbfb8aa3b, v91
	v_exp_f32_e32 v90, v90
	v_exp_f32_e32 v91, v91
	s_nop 0
	v_pk_add_f32 v[94:95], v[90:91], 1.0 op_sel_hi:[1,0]
	v_rcp_f32_e32 v90, v92
	s_nop 0
	v_cvt_pk_bf16_f32 v90, v90, v93
	v_rcp_f32_e32 v91, v95
	v_pk_mul_f32 v[84:85], v[84:85], v[96:97] op_sel_hi:[1,0]
	v_mul_f32_e32 v84, 0xbfb8aa3b, v84
	v_mul_f32_e32 v85, 0xbfb8aa3b, v85
	v_exp_f32_e32 v84, v84
	v_exp_f32_e32 v85, v85
	v_rcp_f32_e32 v92, v94
	s_nop 0
	v_cvt_pk_bf16_f32 v91, v92, v91
	v_lshl_add_u64 v[92:93], s[54:55], 0, v[98:99]
	v_lshl_add_u64 v[92:93], v[92:93], 0, v[120:121]
	v_pk_add_f32 v[84:85], v[84:85], 1.0 op_sel_hi:[1,0]
	global_store_dwordx4 v[92:93], v[88:91], off
	v_pk_mul_f32 v[86:87], v[86:87], v[96:97] op_sel_hi:[1,0]
	v_pk_mul_f32 v[82:83], v[82:83], v[96:97] op_sel_hi:[1,0]
	v_pk_mul_f32 v[88:89], v[80:81], v[96:97] op_sel_hi:[1,0]
	v_mul_f32_e32 v82, 0xbfb8aa3b, v82
	v_mul_f32_e32 v83, 0xbfb8aa3b, v83
	v_rcp_f32_e32 v85, v85
	v_mul_f32_e32 v81, 0xbfb8aa3b, v87
	v_mul_f32_e32 v80, 0xbfb8aa3b, v86
	v_exp_f32_e32 v80, v80
	v_exp_f32_e32 v81, v81
	s_nop 0
	v_pk_add_f32 v[86:87], v[80:81], 1.0 op_sel_hi:[1,0]
	v_rcp_f32_e32 v80, v84
	s_nop 0
	v_cvt_pk_bf16_f32 v80, v80, v85
	v_mul_f32_e32 v85, 0xbfb8aa3b, v89
	v_mul_f32_e32 v84, 0xbfb8aa3b, v88
	v_exp_f32_e32 v84, v84
	v_exp_f32_e32 v85, v85
	v_rcp_f32_e32 v81, v87
	v_pk_add_f32 v[84:85], v[84:85], 1.0 op_sel_hi:[1,0]
	v_rcp_f32_e32 v86, v86
	s_nop 0
	v_cvt_pk_bf16_f32 v81, v86, v81
	v_rcp_f32_e32 v85, v85
	v_exp_f32_e32 v82, v82
	v_exp_f32_e32 v83, v83
	s_nop 0
	v_pk_add_f32 v[86:87], v[82:83], 1.0 op_sel_hi:[1,0]
	v_rcp_f32_e32 v82, v84
	s_nop 0
	v_cvt_pk_bf16_f32 v82, v82, v85
	v_rcp_f32_e32 v83, v87
	v_rcp_f32_e32 v84, v86
	s_nop 0
	v_cvt_pk_bf16_f32 v83, v84, v83
	global_store_dwordx4 v[92:93], v[80:83], off offset:256
	global_load_dword v80, v[144:145], off offset:192
	s_nop 0
	v_or_b32_e32 v82, 48, v146
	v_ashrrev_i32_e32 v83, 31, v82
	v_lshlrev_b64 v[82:83], 11, v[82:83]
	s_waitcnt vmcnt(0)
; DI unsigned pk2(float lo, float hi) { f32x2_t v = {lo, hi}; bf16x2_t b = __builtin_convertvector(v, bf16x2_t); return __builtin_bit_cast(unsigned, b); }
; DI float sigmoidf_(float x) { return 1.0f / (1.0f + __expf(-x)); }
;     DI void operator()(AccRef acc, const Unit& u, int wr, int wc, int fr, int fq) const {
;     ...
;                 const int row = row0 + ai * HALF + m * 16; const float rs = rsqrtf(SS0[row] * (1.0f / DM) + EPSN);
; #pragma unroll
;                 for (int bj = 0; bj < 2; ++bj) {
;                     const f32x4 v0 = acc[ai][bj][m][0] * rs, v1 = acc[ai][bj][m][1] * rs;
;                     u32x4 w; w.x = pk2(sigmoidf_(v0[0]), sigmoidf_(v0[1])); w.y = pk2(sigmoidf_(v0[2]), sigmoidf_(v0[3])); w.z = pk2(sigmoidf_(v1[0]), sigmoidf_(v1[1])); w.w = pk2(sigmoidf_(v1[2]), sigmoidf_(v1[3]));
;                     *(u32x4*)(D + (size_t)row * DM + col0 + bj * HALF) = w;
	v_fmamk_f32 v80, v80, 0x3a800000, v172
	v_mul_f32_e32 v81, 0x4b800000, v80
	v_cmp_gt_f32_e32 vcc, s62, v80
	s_nop 1
	v_cndmask_b32_e32 v80, v80, v81, vcc
	v_rsq_f32_e32 v80, v80
	s_nop 0
	v_mul_f32_e32 v81, 0x45800000, v80
	v_cndmask_b32_e32 v80, v80, v81, vcc
	v_pk_mul_f32 v[76:77], v[76:77], v[80:81] op_sel_hi:[1,0]
	s_nop 0
	v_mul_f32_e32 v76, 0xbfb8aa3b, v76
	v_mul_f32_e32 v77, 0xbfb8aa3b, v77
	v_exp_f32_e32 v76, v76
	v_exp_f32_e32 v77, v77
	s_nop 0
	v_pk_add_f32 v[76:77], v[76:77], 1.0 op_sel_hi:[1,0]
	s_nop 0
	v_pk_mul_f32 v[84:85], v[72:73], v[80:81] op_sel_hi:[1,0]
	v_pk_mul_f32 v[78:79], v[78:79], v[80:81] op_sel_hi:[1,0]
	v_pk_mul_f32 v[74:75], v[74:75], v[80:81] op_sel_hi:[1,0]
	v_rcp_f32_e32 v77, v77
	v_mul_f32_e32 v73, 0xbfb8aa3b, v79
	v_mul_f32_e32 v72, 0xbfb8aa3b, v78
	v_exp_f32_e32 v72, v72
	v_exp_f32_e32 v73, v73
	s_nop 0
	v_pk_add_f32 v[78:79], v[72:73], 1.0 op_sel_hi:[1,0]
	v_rcp_f32_e32 v72, v76
	s_nop 0
	v_cvt_pk_bf16_f32 v72, v72, v77
	v_mul_f32_e32 v77, 0xbfb8aa3b, v85
	v_mul_f32_e32 v76, 0xbfb8aa3b, v84
	v_exp_f32_e32 v76, v76
	v_exp_f32_e32 v77, v77
	v_rcp_f32_e32 v73, v79
	v_pk_add_f32 v[76:77], v[76:77], 1.0 op_sel_hi:[1,0]
	v_rcp_f32_e32 v78, v78
	s_nop 0
	v_cvt_pk_bf16_f32 v73, v78, v73
	v_rcp_f32_e32 v77, v77
	v_mul_f32_e32 v74, 0xbfb8aa3b, v74
	v_mul_f32_e32 v75, 0xbfb8aa3b, v75
	v_exp_f32_e32 v74, v74
	v_exp_f32_e32 v75, v75
	s_nop 0
	v_pk_add_f32 v[78:79], v[74:75], 1.0 op_sel_hi:[1,0]
	v_rcp_f32_e32 v74, v76
	s_nop 0
	v_cvt_pk_bf16_f32 v74, v74, v77
	v_rcp_f32_e32 v75, v79
	v_pk_mul_f32 v[68:69], v[68:69], v[80:81] op_sel_hi:[1,0]
	v_mul_f32_e32 v68, 0xbfb8aa3b, v68
	v_mul_f32_e32 v69, 0xbfb8aa3b, v69
	v_exp_f32_e32 v68, v68
	v_exp_f32_e32 v69, v69
	v_rcp_f32_e32 v76, v78
	s_nop 0
	v_cvt_pk_bf16_f32 v75, v76, v75
	v_lshl_add_u64 v[76:77], s[54:55], 0, v[82:83]
	v_lshl_add_u64 v[76:77], v[76:77], 0, v[120:121]
	v_pk_add_f32 v[68:69], v[68:69], 1.0 op_sel_hi:[1,0]
	global_store_dwordx4 v[76:77], v[72:75], off
	v_pk_mul_f32 v[70:71], v[70:71], v[80:81] op_sel_hi:[1,0]
	v_pk_mul_f32 v[66:67], v[66:67], v[80:81] op_sel_hi:[1,0]
	v_pk_mul_f32 v[72:73], v[64:65], v[80:81] op_sel_hi:[1,0]
	v_mul_f32_e32 v66, 0xbfb8aa3b, v66
	v_mul_f32_e32 v67, 0xbfb8aa3b, v67
	v_rcp_f32_e32 v69, v69
	v_mul_f32_e32 v65, 0xbfb8aa3b, v71
	v_mul_f32_e32 v64, 0xbfb8aa3b, v70
	v_exp_f32_e32 v64, v64
	v_exp_f32_e32 v65, v65
	s_nop 0
	v_pk_add_f32 v[70:71], v[64:65], 1.0 op_sel_hi:[1,0]
	v_rcp_f32_e32 v64, v68
	s_nop 0
	v_cvt_pk_bf16_f32 v64, v64, v69
	v_mul_f32_e32 v69, 0xbfb8aa3b, v73
	v_mul_f32_e32 v68, 0xbfb8aa3b, v72
	v_exp_f32_e32 v68, v68
	v_exp_f32_e32 v69, v69
	v_rcp_f32_e32 v65, v71
	v_pk_add_f32 v[68:69], v[68:69], 1.0 op_sel_hi:[1,0]
	v_rcp_f32_e32 v70, v70
	s_nop 0
	v_cvt_pk_bf16_f32 v65, v70, v65
	v_rcp_f32_e32 v69, v69
	v_exp_f32_e32 v66, v66
	v_exp_f32_e32 v67, v67
	s_nop 0
	v_pk_add_f32 v[70:71], v[66:67], 1.0 op_sel_hi:[1,0]
	v_rcp_f32_e32 v66, v68
	s_nop 0
	v_cvt_pk_bf16_f32 v66, v66, v69
	v_rcp_f32_e32 v67, v71
	v_rcp_f32_e32 v68, v70
	s_nop 0
	v_cvt_pk_bf16_f32 v67, v68, v67
	global_store_dwordx4 v[76:77], v[64:67], off offset:256
	global_load_dword v64, v[144:145], off offset:512
	s_waitcnt vmcnt(0)
	v_fmamk_f32 v64, v64, 0x3a800000, v172
	v_mul_f32_e32 v65, 0x4b800000, v64
	v_cmp_gt_f32_e32 vcc, s62, v64
	s_nop 1
	v_cndmask_b32_e32 v64, v64, v65, vcc
	v_rsq_f32_e32 v64, v64
	s_nop 0
	v_mul_f32_e32 v65, 0x45800000, v64
	v_cndmask_b32_e32 v64, v64, v65, vcc
	v_pk_mul_f32 v[60:61], v[60:61], v[64:65] op_sel_hi:[1,0]
	s_nop 0
	v_mul_f32_e32 v60, 0xbfb8aa3b, v60
	v_mul_f32_e32 v61, 0xbfb8aa3b, v61
	v_exp_f32_e32 v60, v60
	v_exp_f32_e32 v61, v61
	s_nop 0
	v_pk_add_f32 v[60:61], v[60:61], 1.0 op_sel_hi:[1,0]
	s_nop 0
	v_pk_mul_f32 v[66:67], v[56:57], v[64:65] op_sel_hi:[1,0]
	v_pk_mul_f32 v[62:63], v[62:63], v[64:65] op_sel_hi:[1,0]
	v_pk_mul_f32 v[58:59], v[58:59], v[64:65] op_sel_hi:[1,0]
	v_rcp_f32_e32 v61, v61
	v_mul_f32_e32 v57, 0xbfb8aa3b, v63
	v_mul_f32_e32 v56, 0xbfb8aa3b, v62
	v_exp_f32_e32 v56, v56
	v_exp_f32_e32 v57, v57
	s_nop 0
	v_pk_add_f32 v[62:63], v[56:57], 1.0 op_sel_hi:[1,0]
	v_rcp_f32_e32 v56, v60
	s_nop 0
	v_cvt_pk_bf16_f32 v56, v56, v61
	v_mul_f32_e32 v61, 0xbfb8aa3b, v67
	v_mul_f32_e32 v60, 0xbfb8aa3b, v66
	v_exp_f32_e32 v60, v60
	v_exp_f32_e32 v61, v61
	v_rcp_f32_e32 v57, v63
	v_pk_add_f32 v[60:61], v[60:61], 1.0 op_sel_hi:[1,0]
	v_rcp_f32_e32 v62, v62
	s_nop 0
	v_cvt_pk_bf16_f32 v57, v62, v57
	v_rcp_f32_e32 v61, v61
	v_mul_f32_e32 v58, 0xbfb8aa3b, v58
	v_mul_f32_e32 v59, 0xbfb8aa3b, v59
	v_exp_f32_e32 v58, v58
	v_exp_f32_e32 v59, v59
	s_nop 0
	v_pk_add_f32 v[62:63], v[58:59], 1.0 op_sel_hi:[1,0]
	v_rcp_f32_e32 v58, v60
	s_nop 0
	v_cvt_pk_bf16_f32 v58, v58, v61
	v_rcp_f32_e32 v59, v63
	s_mov_b64 s[0:1], 0x40000
	v_pk_mul_f32 v[52:53], v[52:53], v[64:65] op_sel_hi:[1,0]
	v_mul_f32_e32 v52, 0xbfb8aa3b, v52
	v_mul_f32_e32 v53, 0xbfb8aa3b, v53
	v_exp_f32_e32 v52, v52
	v_exp_f32_e32 v53, v53
	v_rcp_f32_e32 v60, v62
	s_nop 0
	v_cvt_pk_bf16_f32 v59, v60, v59
	v_lshl_add_u64 v[60:61], v[116:117], 0, s[0:1]
	s_mov_b32 s0, 0x40000
	v_add_co_u32_e32 v62, vcc, s0, v116
	v_pk_add_f32 v[52:53], v[52:53], 1.0 op_sel_hi:[1,0]
	s_nop 0
	v_addc_co_u32_e32 v63, vcc, 0, v117, vcc
	global_store_dwordx4 v[62:63], v[56:59], off
	v_pk_mul_f32 v[54:55], v[54:55], v[64:65] op_sel_hi:[1,0]
	v_pk_mul_f32 v[50:51], v[50:51], v[64:65] op_sel_hi:[1,0]
	v_pk_mul_f32 v[56:57], v[48:49], v[64:65] op_sel_hi:[1,0]
	v_mul_f32_e32 v50, 0xbfb8aa3b, v50
	v_mul_f32_e32 v51, 0xbfb8aa3b, v51
	v_rcp_f32_e32 v53, v53
	v_mul_f32_e32 v49, 0xbfb8aa3b, v55
	v_mul_f32_e32 v48, 0xbfb8aa3b, v54
	v_exp_f32_e32 v48, v48
	v_exp_f32_e32 v49, v49
	s_nop 0
	v_pk_add_f32 v[54:55], v[48:49], 1.0 op_sel_hi:[1,0]
	v_rcp_f32_e32 v48, v52
	s_nop 0
	v_cvt_pk_bf16_f32 v48, v48, v53
	v_mul_f32_e32 v53, 0xbfb8aa3b, v57
	v_mul_f32_e32 v52, 0xbfb8aa3b, v56
	v_exp_f32_e32 v52, v52
	v_exp_f32_e32 v53, v53
	v_rcp_f32_e32 v49, v55
	v_pk_add_f32 v[52:53], v[52:53], 1.0 op_sel_hi:[1,0]
	v_rcp_f32_e32 v54, v54
	s_nop 0
	v_cvt_pk_bf16_f32 v49, v54, v49
	v_rcp_f32_e32 v53, v53
	v_exp_f32_e32 v50, v50
	v_exp_f32_e32 v51, v51
	s_nop 0
	v_pk_add_f32 v[54:55], v[50:51], 1.0 op_sel_hi:[1,0]
	v_rcp_f32_e32 v50, v52
	s_nop 0
	v_cvt_pk_bf16_f32 v50, v50, v53
	v_rcp_f32_e32 v51, v55
	v_rcp_f32_e32 v52, v54
	s_nop 0
	v_cvt_pk_bf16_f32 v51, v52, v51
	global_store_dwordx4 v[60:61], v[48:51], off offset:256
	global_load_dword v48, v[144:145], off offset:576
	s_waitcnt vmcnt(0)
; DI unsigned pk2(float lo, float hi) { f32x2_t v = {lo, hi}; bf16x2_t b = __builtin_convertvector(v, bf16x2_t); return __builtin_bit_cast(unsigned, b); }
; DI float sigmoidf_(float x) { return 1.0f / (1.0f + __expf(-x)); }
;     DI void operator()(AccRef acc, const Unit& u, int wr, int wc, int fr, int fq) const {
;     ...
;                 const int row = row0 + ai * HALF + m * 16; const float rs = rsqrtf(SS0[row] * (1.0f / DM) + EPSN);
; #pragma unroll
;                 for (int bj = 0; bj < 2; ++bj) {
;                     const f32x4 v0 = acc[ai][bj][m][0] * rs, v1 = acc[ai][bj][m][1] * rs;
;                     u32x4 w; w.x = pk2(sigmoidf_(v0[0]), sigmoidf_(v0[1])); w.y = pk2(sigmoidf_(v0[2]), sigmoidf_(v0[3])); w.z = pk2(sigmoidf_(v1[0]), sigmoidf_(v1[1])); w.w = pk2(sigmoidf_(v1[2]), sigmoidf_(v1[3]));
;                     *(u32x4*)(D + (size_t)row * DM + col0 + bj * HALF) = w;
	v_fmamk_f32 v48, v48, 0x3a800000, v172
	v_mul_f32_e32 v49, 0x4b800000, v48
	v_cmp_gt_f32_e32 vcc, s62, v48
	s_nop 1
	v_cndmask_b32_e32 v48, v48, v49, vcc
	v_rsq_f32_e32 v48, v48
	s_nop 0
	v_mul_f32_e32 v49, 0x45800000, v48
	v_cndmask_b32_e32 v48, v48, v49, vcc
	v_pk_mul_f32 v[44:45], v[44:45], v[48:49] op_sel_hi:[1,0]
	s_nop 0
	v_mul_f32_e32 v44, 0xbfb8aa3b, v44
	v_mul_f32_e32 v45, 0xbfb8aa3b, v45
	v_exp_f32_e32 v44, v44
	v_exp_f32_e32 v45, v45
	s_nop 0
	v_pk_add_f32 v[44:45], v[44:45], 1.0 op_sel_hi:[1,0]
	s_nop 0
	v_pk_mul_f32 v[50:51], v[40:41], v[48:49] op_sel_hi:[1,0]
	v_pk_mul_f32 v[46:47], v[46:47], v[48:49] op_sel_hi:[1,0]
	v_pk_mul_f32 v[42:43], v[42:43], v[48:49] op_sel_hi:[1,0]
	v_rcp_f32_e32 v45, v45
	v_mul_f32_e32 v41, 0xbfb8aa3b, v47
	v_mul_f32_e32 v40, 0xbfb8aa3b, v46
	v_exp_f32_e32 v40, v40
	v_exp_f32_e32 v41, v41
	s_nop 0
	v_pk_add_f32 v[46:47], v[40:41], 1.0 op_sel_hi:[1,0]
	v_rcp_f32_e32 v40, v44
	s_nop 0
	v_cvt_pk_bf16_f32 v40, v40, v45
	v_mul_f32_e32 v45, 0xbfb8aa3b, v51
	v_mul_f32_e32 v44, 0xbfb8aa3b, v50
	v_exp_f32_e32 v44, v44
	v_exp_f32_e32 v45, v45
	v_rcp_f32_e32 v41, v47
	v_pk_add_f32 v[44:45], v[44:45], 1.0 op_sel_hi:[1,0]
	v_rcp_f32_e32 v46, v46
	s_nop 0
	v_cvt_pk_bf16_f32 v41, v46, v41
	v_rcp_f32_e32 v45, v45
	v_mul_f32_e32 v42, 0xbfb8aa3b, v42
	v_mul_f32_e32 v43, 0xbfb8aa3b, v43
	v_exp_f32_e32 v42, v42
	v_exp_f32_e32 v43, v43
	s_nop 0
	v_pk_add_f32 v[46:47], v[42:43], 1.0 op_sel_hi:[1,0]
	v_rcp_f32_e32 v42, v44
	s_nop 0
	v_cvt_pk_bf16_f32 v42, v42, v45
	v_rcp_f32_e32 v43, v47
	s_mov_b64 s[0:1], 0x48000
	v_pk_mul_f32 v[36:37], v[36:37], v[48:49] op_sel_hi:[1,0]
	v_mul_f32_e32 v36, 0xbfb8aa3b, v36
	v_mul_f32_e32 v37, 0xbfb8aa3b, v37
	v_exp_f32_e32 v36, v36
	v_exp_f32_e32 v37, v37
	v_rcp_f32_e32 v44, v46
	s_nop 0
	v_cvt_pk_bf16_f32 v43, v44, v43
	v_lshl_add_u64 v[44:45], v[116:117], 0, s[0:1]
	s_mov_b32 s0, 0x48000
	v_add_co_u32_e32 v46, vcc, s0, v116
	v_pk_add_f32 v[36:37], v[36:37], 1.0 op_sel_hi:[1,0]
	s_nop 0
	v_addc_co_u32_e32 v47, vcc, 0, v117, vcc
	global_store_dwordx4 v[46:47], v[40:43], off
	v_pk_mul_f32 v[38:39], v[38:39], v[48:49] op_sel_hi:[1,0]
	v_pk_mul_f32 v[34:35], v[34:35], v[48:49] op_sel_hi:[1,0]
	v_pk_mul_f32 v[40:41], v[32:33], v[48:49] op_sel_hi:[1,0]
	v_mul_f32_e32 v34, 0xbfb8aa3b, v34
	v_mul_f32_e32 v35, 0xbfb8aa3b, v35
	v_rcp_f32_e32 v37, v37
	v_mul_f32_e32 v33, 0xbfb8aa3b, v39
	v_mul_f32_e32 v32, 0xbfb8aa3b, v38
	v_exp_f32_e32 v32, v32
	v_exp_f32_e32 v33, v33
	s_nop 0
	v_pk_add_f32 v[38:39], v[32:33], 1.0 op_sel_hi:[1,0]
	v_rcp_f32_e32 v32, v36
	s_nop 0
	v_cvt_pk_bf16_f32 v32, v32, v37
	v_mul_f32_e32 v37, 0xbfb8aa3b, v41
	v_mul_f32_e32 v36, 0xbfb8aa3b, v40
	v_exp_f32_e32 v36, v36
	v_exp_f32_e32 v37, v37
	v_rcp_f32_e32 v33, v39
	v_pk_add_f32 v[36:37], v[36:37], 1.0 op_sel_hi:[1,0]
	v_rcp_f32_e32 v38, v38
	s_nop 0
	v_cvt_pk_bf16_f32 v33, v38, v33
	v_rcp_f32_e32 v37, v37
	v_exp_f32_e32 v34, v34
	v_exp_f32_e32 v35, v35
	s_nop 0
	v_pk_add_f32 v[38:39], v[34:35], 1.0 op_sel_hi:[1,0]
	v_rcp_f32_e32 v34, v36
	s_nop 0
	v_cvt_pk_bf16_f32 v34, v34, v37
	v_rcp_f32_e32 v35, v39
	v_rcp_f32_e32 v36, v38
	s_nop 0
	v_cvt_pk_bf16_f32 v35, v36, v35
	global_store_dwordx4 v[44:45], v[32:35], off offset:256
	global_load_dword v32, v[144:145], off offset:640
	s_waitcnt vmcnt(0)
; #define PG8_BAR __builtin_amdgcn_s_barrier()
; DI unsigned pk2(float lo, float hi) { f32x2_t v = {lo, hi}; bf16x2_t b = __builtin_convertvector(v, bf16x2_t); return __builtin_bit_cast(unsigned, b); }
; DI float sigmoidf_(float x) { return 1.0f / (1.0f + __expf(-x)); }
; template <class Epi, class Sched, bool ALIGN_EPI = false, bool SP2 = false>
; __device__ __forceinline__ void gemm_phase(PG8_LAS unsigned char* lds, const Gemm g, const Sched& S, const Epi& E) {
;     ...
;         if constexpr (ALIGN_EPI) { if (wr == 0) PG8_BAR; }
;         if constexpr (!Epi::AFTER_DRAIN) { E(acc, cur, wr, wc, fr, fq); S.done(cur); }
;         if (!has_next) break;
; #pragma unroll
;         for (int a = 0; a < 2; ++a)
; #pragma unroll
;             for (int b = 0; b < 2; ++b)
; #pragma unroll
;                 for (int m = 0; m < 4; ++m)
; #pragma unroll
;                     for (int n = 0; n < 2; ++n) acc[a][b][m][n] = (f32x4){0.f, 0.f, 0.f, 0.f};
;         cur = nxt; cA = nA; cB = nB; ++ui;
;         if constexpr (ALIGN_EPI) { if (wr == 1) PG8_BAR; }
;     DI void operator()(AccRef acc, const Unit& u, int wr, int wc, int fr, int fq) const {
;     ...
;                 const int row = row0 + ai * HALF + m * 16; const float rs = rsqrtf(SS0[row] * (1.0f / DM) + EPSN);
; #pragma unroll
;                 for (int bj = 0; bj < 2; ++bj) {
;                     const f32x4 v0 = acc[ai][bj][m][0] * rs, v1 = acc[ai][bj][m][1] * rs;
;                     u32x4 w; w.x = pk2(sigmoidf_(v0[0]), sigmoidf_(v0[1])); w.y = pk2(sigmoidf_(v0[2]), sigmoidf_(v0[3])); w.z = pk2(sigmoidf_(v1[0]), sigmoidf_(v1[1])); w.w = pk2(sigmoidf_(v1[2]), sigmoidf_(v1[3]));
;                     *(u32x4*)(D + (size_t)row * DM + col0 + bj * HALF) = w;
	v_fmamk_f32 v32, v32, 0x3a800000, v172
	v_mul_f32_e32 v33, 0x4b800000, v32
	v_cmp_gt_f32_e32 vcc, s62, v32
	s_nop 1
	v_cndmask_b32_e32 v32, v32, v33, vcc
	v_rsq_f32_e32 v32, v32
	s_nop 0
	v_mul_f32_e32 v33, 0x45800000, v32
	v_cndmask_b32_e32 v32, v32, v33, vcc
	v_pk_mul_f32 v[28:29], v[28:29], v[32:33] op_sel_hi:[1,0]
	s_nop 0
	v_mul_f32_e32 v28, 0xbfb8aa3b, v28
	v_mul_f32_e32 v29, 0xbfb8aa3b, v29
	v_exp_f32_e32 v28, v28
	v_exp_f32_e32 v29, v29
	s_nop 0
	v_pk_add_f32 v[28:29], v[28:29], 1.0 op_sel_hi:[1,0]
	s_nop 0
	v_pk_mul_f32 v[34:35], v[24:25], v[32:33] op_sel_hi:[1,0]
	v_pk_mul_f32 v[30:31], v[30:31], v[32:33] op_sel_hi:[1,0]
	v_pk_mul_f32 v[26:27], v[26:27], v[32:33] op_sel_hi:[1,0]
	v_rcp_f32_e32 v29, v29
	v_mul_f32_e32 v25, 0xbfb8aa3b, v31
	v_mul_f32_e32 v24, 0xbfb8aa3b, v30
	v_exp_f32_e32 v24, v24
	v_exp_f32_e32 v25, v25
	s_nop 0
	v_pk_add_f32 v[30:31], v[24:25], 1.0 op_sel_hi:[1,0]
	v_rcp_f32_e32 v24, v28
	s_nop 0
	v_cvt_pk_bf16_f32 v24, v24, v29
	v_mul_f32_e32 v29, 0xbfb8aa3b, v35
	v_mul_f32_e32 v28, 0xbfb8aa3b, v34
	v_exp_f32_e32 v28, v28
	v_exp_f32_e32 v29, v29
	v_rcp_f32_e32 v25, v31
	v_pk_add_f32 v[28:29], v[28:29], 1.0 op_sel_hi:[1,0]
	v_rcp_f32_e32 v30, v30
	s_nop 0
	v_cvt_pk_bf16_f32 v25, v30, v25
	v_rcp_f32_e32 v29, v29
	v_mul_f32_e32 v26, 0xbfb8aa3b, v26
	v_mul_f32_e32 v27, 0xbfb8aa3b, v27
	v_exp_f32_e32 v26, v26
	v_exp_f32_e32 v27, v27
	s_nop 0
	v_pk_add_f32 v[30:31], v[26:27], 1.0 op_sel_hi:[1,0]
	v_rcp_f32_e32 v26, v28
	s_nop 0
	v_cvt_pk_bf16_f32 v26, v26, v29
	v_rcp_f32_e32 v27, v31
	v_pk_mul_f32 v[20:21], v[20:21], v[32:33] op_sel_hi:[1,0]
	v_mul_f32_e32 v20, 0xbfb8aa3b, v20
	v_mul_f32_e32 v21, 0xbfb8aa3b, v21
	v_exp_f32_e32 v20, v20
	v_exp_f32_e32 v21, v21
	v_rcp_f32_e32 v28, v30
	v_add_co_u32_e32 v30, vcc, s63, v116
	v_cvt_pk_bf16_f32 v27, v28, v27
	s_nop 0
	v_addc_co_u32_e32 v31, vcc, 0, v117, vcc
	v_pk_add_f32 v[20:21], v[20:21], 1.0 op_sel_hi:[1,0]
	global_store_dwordx4 v[30:31], v[24:27], off
	v_pk_mul_f32 v[22:23], v[22:23], v[32:33] op_sel_hi:[1,0]
	v_pk_mul_f32 v[18:19], v[18:19], v[32:33] op_sel_hi:[1,0]
	v_pk_mul_f32 v[24:25], v[16:17], v[32:33] op_sel_hi:[1,0]
	v_mul_f32_e32 v18, 0xbfb8aa3b, v18
	v_mul_f32_e32 v19, 0xbfb8aa3b, v19
	v_rcp_f32_e32 v21, v21
	v_mul_f32_e32 v17, 0xbfb8aa3b, v23
	v_mul_f32_e32 v16, 0xbfb8aa3b, v22
	v_exp_f32_e32 v16, v16
	v_exp_f32_e32 v17, v17
	s_nop 0
	v_pk_add_f32 v[22:23], v[16:17], 1.0 op_sel_hi:[1,0]
	v_rcp_f32_e32 v16, v20
	s_nop 0
	v_cvt_pk_bf16_f32 v16, v16, v21
	v_mul_f32_e32 v21, 0xbfb8aa3b, v25
	v_mul_f32_e32 v20, 0xbfb8aa3b, v24
	v_exp_f32_e32 v20, v20
	v_exp_f32_e32 v21, v21
	v_rcp_f32_e32 v17, v23
	v_pk_add_f32 v[20:21], v[20:21], 1.0 op_sel_hi:[1,0]
	v_rcp_f32_e32 v22, v22
	s_nop 0
	v_cvt_pk_bf16_f32 v17, v22, v17
	v_rcp_f32_e32 v21, v21
	v_exp_f32_e32 v18, v18
	v_exp_f32_e32 v19, v19
	s_nop 0
	v_pk_add_f32 v[22:23], v[18:19], 1.0 op_sel_hi:[1,0]
	v_rcp_f32_e32 v18, v20
	s_nop 0
	v_cvt_pk_bf16_f32 v18, v18, v21
	v_lshl_add_u64 v[28:29], v[116:117], 0, s[22:23]
	v_rcp_f32_e32 v19, v23
	v_rcp_f32_e32 v20, v22
	s_nop 0
	v_cvt_pk_bf16_f32 v19, v20, v19
	global_store_dwordx4 v[28:29], v[16:19], off offset:256
	global_load_dword v16, v[144:145], off offset:704
	s_waitcnt vmcnt(0)
	v_fmamk_f32 v16, v16, 0x3a800000, v172
	v_mul_f32_e32 v17, 0x4b800000, v16
	v_cmp_gt_f32_e32 vcc, s62, v16
	s_nop 1
	v_cndmask_b32_e32 v16, v16, v17, vcc
	v_rsq_f32_e32 v16, v16
	s_nop 0
	v_mul_f32_e32 v17, 0x45800000, v16
	v_cndmask_b32_e32 v16, v16, v17, vcc
	v_pk_mul_f32 v[12:13], v[12:13], v[16:17] op_sel_hi:[1,0]
	s_nop 0
	v_mul_f32_e32 v12, 0xbfb8aa3b, v12
	v_mul_f32_e32 v13, 0xbfb8aa3b, v13
	v_exp_f32_e32 v12, v12
	v_exp_f32_e32 v13, v13
	s_nop 0
	v_pk_add_f32 v[12:13], v[12:13], 1.0 op_sel_hi:[1,0]
	s_nop 0
	v_pk_mul_f32 v[18:19], v[8:9], v[16:17] op_sel_hi:[1,0]
	v_pk_mul_f32 v[14:15], v[14:15], v[16:17] op_sel_hi:[1,0]
	v_pk_mul_f32 v[10:11], v[10:11], v[16:17] op_sel_hi:[1,0]
	v_rcp_f32_e32 v13, v13
	v_mul_f32_e32 v9, 0xbfb8aa3b, v15
	v_mul_f32_e32 v8, 0xbfb8aa3b, v14
	v_exp_f32_e32 v8, v8
	v_exp_f32_e32 v9, v9
	s_nop 0
	v_pk_add_f32 v[14:15], v[8:9], 1.0 op_sel_hi:[1,0]
	v_rcp_f32_e32 v8, v12
	s_nop 0
	v_cvt_pk_bf16_f32 v8, v8, v13
	v_mul_f32_e32 v13, 0xbfb8aa3b, v19
	v_mul_f32_e32 v12, 0xbfb8aa3b, v18
	v_exp_f32_e32 v12, v12
	v_exp_f32_e32 v13, v13
	v_rcp_f32_e32 v9, v15
	v_pk_add_f32 v[12:13], v[12:13], 1.0 op_sel_hi:[1,0]
	v_rcp_f32_e32 v14, v14
	s_nop 0
	v_cvt_pk_bf16_f32 v9, v14, v9
	v_rcp_f32_e32 v13, v13
	v_mul_f32_e32 v10, 0xbfb8aa3b, v10
	v_mul_f32_e32 v11, 0xbfb8aa3b, v11
	v_exp_f32_e32 v10, v10
	v_exp_f32_e32 v11, v11
	s_nop 0
	v_pk_add_f32 v[14:15], v[10:11], 1.0 op_sel_hi:[1,0]
	v_rcp_f32_e32 v10, v12
	s_nop 0
	v_cvt_pk_bf16_f32 v10, v10, v13
	v_rcp_f32_e32 v11, v15
	v_pk_mul_f32 v[4:5], v[4:5], v[16:17] op_sel_hi:[1,0]
	v_mul_f32_e32 v4, 0xbfb8aa3b, v4
	v_mul_f32_e32 v5, 0xbfb8aa3b, v5
	v_exp_f32_e32 v4, v4
	v_exp_f32_e32 v5, v5
	v_rcp_f32_e32 v12, v14
	v_add_co_u32_e32 v14, vcc, s68, v116
	v_cvt_pk_bf16_f32 v11, v12, v11
	s_nop 0
	v_addc_co_u32_e32 v15, vcc, 0, v117, vcc
	v_pk_add_f32 v[4:5], v[4:5], 1.0 op_sel_hi:[1,0]
	global_store_dwordx4 v[14:15], v[8:11], off
	v_pk_mul_f32 v[6:7], v[6:7], v[16:17] op_sel_hi:[1,0]
	v_pk_mul_f32 v[2:3], v[2:3], v[16:17] op_sel_hi:[1,0]
	v_pk_mul_f32 v[8:9], v[0:1], v[16:17] op_sel_hi:[1,0]
	v_mul_f32_e32 v2, 0xbfb8aa3b, v2
	v_mul_f32_e32 v3, 0xbfb8aa3b, v3
	v_rcp_f32_e32 v5, v5
	v_mul_f32_e32 v1, 0xbfb8aa3b, v7
	v_mul_f32_e32 v0, 0xbfb8aa3b, v6
	v_exp_f32_e32 v0, v0
	v_exp_f32_e32 v1, v1
	s_nop 0
	v_pk_add_f32 v[6:7], v[0:1], 1.0 op_sel_hi:[1,0]
	v_rcp_f32_e32 v0, v4
	s_nop 0
	v_cvt_pk_bf16_f32 v0, v0, v5
	v_mul_f32_e32 v5, 0xbfb8aa3b, v9
	v_mul_f32_e32 v4, 0xbfb8aa3b, v8
	v_exp_f32_e32 v4, v4
	v_exp_f32_e32 v5, v5
	v_rcp_f32_e32 v1, v7
	v_pk_add_f32 v[4:5], v[4:5], 1.0 op_sel_hi:[1,0]
	v_rcp_f32_e32 v6, v6
	s_nop 0
	v_cvt_pk_bf16_f32 v1, v6, v1
	v_rcp_f32_e32 v5, v5
	v_exp_f32_e32 v2, v2
	v_exp_f32_e32 v3, v3
	s_nop 0
	v_pk_add_f32 v[6:7], v[2:3], 1.0 op_sel_hi:[1,0]
	v_rcp_f32_e32 v2, v4
	s_nop 0
	v_cvt_pk_bf16_f32 v2, v2, v5
	v_lshl_add_u64 v[12:13], v[116:117], 0, s[24:25]
	v_rcp_f32_e32 v3, v7
	s_mov_b64 s[0:1], -1
	v_rcp_f32_e32 v4, v6
	s_nop 0
	v_cvt_pk_bf16_f32 v3, v4, v3
	s_andn2_b64 vcc, exec, s[2:3]
	global_store_dwordx4 v[12:13], v[0:3], off offset:256
	s_cbranch_vccnz .LBB0_1239
	s_andn2_b64 vcc, exec, s[16:17]
	s_cbranch_vccnz .LBB0_1238
	s_barrier
	s_branch .LBB0_1238

; DI unsigned pk2(float lo, float hi) { f32x2_t v = {lo, hi}; bf16x2_t b = __builtin_convertvector(v, bf16x2_t); return __builtin_bit_cast(unsigned, b); }
; DI float sigmoidf_(float x) { return 1.0f / (1.0f + __expf(-x)); }
;     DI void operator()(AccRef acc, const Unit& u, int wr, int wc, int fr, int fq) const {
;     ...
;                 const int row = row0 + ai * HALF + m * 16; const float rs = rsqrtf(SS0[row] * (1.0f / DM) + EPSN);
; #pragma unroll
;                 for (int bj = 0; bj < 2; ++bj) {
;                     const f32x4 v0 = acc[ai][bj][m][0] * rs, v1 = acc[ai][bj][m][1] * rs;
;                     u32x4 w; w.x = pk2(sigmoidf_(v0[0]), sigmoidf_(v0[1])); w.y = pk2(sigmoidf_(v0[2]), sigmoidf_(v0[3])); w.z = pk2(sigmoidf_(v1[0]), sigmoidf_(v1[1])); w.w = pk2(sigmoidf_(v1[2]), sigmoidf_(v1[3]));
;                     *(u32x4*)(D + (size_t)row * DM + col0 + bj * HALF) = w;
.LBB0_1298:
	v_lshl_add_u32 v158, s0, 8, v137
	v_ashrrev_i32_e32 v159, 31, v158
	v_lshl_add_u64 v[156:157], v[158:159], 2, s[82:83]
	global_load_dword v160, v[156:157], off
	v_lshlrev_b64 v[172:173], 11, v[158:159]
	s_waitcnt vmcnt(0)
	v_fmamk_f32 v160, v160, 0x3a800000, v171
	v_mul_f32_e32 v162, 0x4b800000, v160
	v_cmp_gt_f32_e32 vcc, s60, v160
	s_nop 1
	v_cndmask_b32_e32 v160, v160, v162, vcc
	v_rsq_f32_e32 v160, v160
	v_lshl_or_b32 v162, s1, 8, v141
	v_ashrrev_i32_e32 v163, 31, v162
	v_mul_f32_e32 v159, 0x45800000, v160
	v_cndmask_b32_e32 v160, v160, v159, vcc
	v_pk_mul_f32 v[124:125], v[124:125], v[160:161] op_sel_hi:[1,0]
	v_pk_mul_f32 v[126:127], v[126:127], v[160:161] op_sel_hi:[1,0]
	v_pk_mul_f32 v[120:121], v[120:121], v[160:161] op_sel_hi:[1,0]
	v_mul_f32_e32 v124, 0xbfb8aa3b, v124
	v_mul_f32_e32 v125, 0xbfb8aa3b, v125
	v_pk_mul_f32 v[122:123], v[122:123], v[160:161] op_sel_hi:[1,0]
	v_mul_f32_e32 v126, 0xbfb8aa3b, v126
	v_mul_f32_e32 v127, 0xbfb8aa3b, v127
	v_mul_f32_e32 v159, 0xbfb8aa3b, v120
	v_mul_f32_e32 v174, 0xbfb8aa3b, v121
	v_exp_f32_e32 v120, v124
	v_exp_f32_e32 v121, v125
	v_mul_f32_e32 v175, 0xbfb8aa3b, v122
	v_mul_f32_e32 v176, 0xbfb8aa3b, v123
	v_exp_f32_e32 v122, v126
	v_exp_f32_e32 v123, v127
	v_exp_f32_e32 v124, v159
	v_exp_f32_e32 v125, v174
	v_pk_add_f32 v[120:121], v[120:121], 1.0 op_sel_hi:[1,0]
	v_exp_f32_e32 v126, v175
	v_pk_add_f32 v[174:175], v[122:123], 1.0 op_sel_hi:[1,0]
	v_pk_add_f32 v[124:125], v[124:125], 1.0 op_sel_hi:[1,0]
	v_rcp_f32_e32 v121, v121
	v_rcp_f32_e32 v120, v120
	s_nop 0
	v_cvt_pk_bf16_f32 v122, v120, v121
	v_rcp_f32_e32 v125, v125
	v_exp_f32_e32 v127, v176
	v_rcp_f32_e32 v120, v175
	v_rcp_f32_e32 v121, v174
	s_nop 0
	v_cvt_pk_bf16_f32 v123, v121, v120
	v_pk_add_f32 v[120:121], v[126:127], 1.0 op_sel_hi:[1,0]
	v_rcp_f32_e32 v124, v124
	s_nop 0
	v_cvt_pk_bf16_f32 v124, v124, v125
	v_rcp_f32_e32 v121, v121
	v_pk_mul_f32 v[116:117], v[116:117], v[160:161] op_sel_hi:[1,0]
	v_mul_f32_e32 v116, 0xbfb8aa3b, v116
	v_lshl_add_u64 v[126:127], s[80:81], 0, v[172:173]
	v_exp_f32_e32 v172, v116
	v_mul_f32_e32 v116, 0xbfb8aa3b, v117
	v_exp_f32_e32 v173, v116
	v_rcp_f32_e32 v120, v120
	s_nop 0
	v_cvt_pk_bf16_f32 v125, v120, v121
	v_lshlrev_b64 v[120:121], 1, v[162:163]
	v_lshl_add_u64 v[116:117], v[126:127], 0, v[120:121]
	global_store_dwordx4 v[116:117], v[122:125], off
	v_pk_mul_f32 v[118:119], v[118:119], v[160:161] op_sel_hi:[1,0]
	v_pk_mul_f32 v[114:115], v[114:115], v[160:161] op_sel_hi:[1,0]
	v_pk_add_f32 v[122:123], v[172:173], 1.0 op_sel_hi:[1,0]
	v_pk_mul_f32 v[124:125], v[112:113], v[160:161] op_sel_hi:[1,0]
	v_mul_f32_e32 v114, 0xbfb8aa3b, v114
	v_mul_f32_e32 v115, 0xbfb8aa3b, v115
	v_exp_f32_e32 v114, v114
	v_rcp_f32_e32 v123, v123
	v_mul_f32_e32 v113, 0xbfb8aa3b, v119
	v_mul_f32_e32 v112, 0xbfb8aa3b, v118
	v_exp_f32_e32 v112, v112
	v_exp_f32_e32 v113, v113
	s_nop 0
	v_pk_add_f32 v[118:119], v[112:113], 1.0 op_sel_hi:[1,0]
	v_rcp_f32_e32 v112, v122
	s_nop 0
	v_cvt_pk_bf16_f32 v112, v112, v123
	v_mul_f32_e32 v122, 0xbfb8aa3b, v124
	v_mul_f32_e32 v123, 0xbfb8aa3b, v125
	v_exp_f32_e32 v122, v122
	v_exp_f32_e32 v123, v123
	v_rcp_f32_e32 v113, v119
	v_pk_add_f32 v[122:123], v[122:123], 1.0 op_sel_hi:[1,0]
	v_rcp_f32_e32 v118, v118
	s_nop 0
	v_cvt_pk_bf16_f32 v113, v118, v113
	v_rcp_f32_e32 v123, v123
	v_exp_f32_e32 v115, v115
	s_nop 0
	v_pk_add_f32 v[118:119], v[114:115], 1.0 op_sel_hi:[1,0]
	v_rcp_f32_e32 v114, v122
	s_nop 0
	v_cvt_pk_bf16_f32 v114, v114, v123
	v_rcp_f32_e32 v115, v119
	v_rcp_f32_e32 v118, v118
	s_nop 0
	v_cvt_pk_bf16_f32 v115, v118, v115
	global_store_dwordx4 v[116:117], v[112:115], off offset:256
	global_load_dword v112, v[156:157], off offset:64
	s_nop 0
	v_or_b32_e32 v114, 16, v158
	v_ashrrev_i32_e32 v115, 31, v114
	v_lshlrev_b64 v[114:115], 11, v[114:115]
	s_waitcnt vmcnt(0)
	v_fmamk_f32 v112, v112, 0x3a800000, v171
	v_mul_f32_e32 v113, 0x4b800000, v112
	v_cmp_gt_f32_e32 vcc, s60, v112
	s_nop 1
	v_cndmask_b32_e32 v112, v112, v113, vcc
	v_rsq_f32_e32 v112, v112
	s_nop 0
	v_mul_f32_e32 v113, 0x45800000, v112
	v_cndmask_b32_e32 v112, v112, v113, vcc
	v_pk_mul_f32 v[108:109], v[108:109], v[112:113] op_sel_hi:[1,0]
	s_nop 0
	v_mul_f32_e32 v108, 0xbfb8aa3b, v108
	v_mul_f32_e32 v109, 0xbfb8aa3b, v109
	v_exp_f32_e32 v108, v108
	v_exp_f32_e32 v109, v109
	s_nop 0
	v_pk_add_f32 v[108:109], v[108:109], 1.0 op_sel_hi:[1,0]
	s_nop 0
	v_pk_mul_f32 v[118:119], v[104:105], v[112:113] op_sel_hi:[1,0]
	v_pk_mul_f32 v[110:111], v[110:111], v[112:113] op_sel_hi:[1,0]
	v_pk_mul_f32 v[106:107], v[106:107], v[112:113] op_sel_hi:[1,0]
	v_rcp_f32_e32 v109, v109
	v_mul_f32_e32 v105, 0xbfb8aa3b, v111
	v_mul_f32_e32 v104, 0xbfb8aa3b, v110
	v_exp_f32_e32 v104, v104
	v_exp_f32_e32 v105, v105
	s_nop 0
	v_pk_add_f32 v[110:111], v[104:105], 1.0 op_sel_hi:[1,0]
	v_rcp_f32_e32 v104, v108
	s_nop 0
	v_cvt_pk_bf16_f32 v104, v104, v109
	v_mul_f32_e32 v109, 0xbfb8aa3b, v119
	v_mul_f32_e32 v108, 0xbfb8aa3b, v118
	v_exp_f32_e32 v108, v108
	v_exp_f32_e32 v109, v109
	v_rcp_f32_e32 v105, v111
	v_pk_add_f32 v[108:109], v[108:109], 1.0 op_sel_hi:[1,0]
	v_rcp_f32_e32 v110, v110
	s_nop 0
	v_cvt_pk_bf16_f32 v105, v110, v105
	v_rcp_f32_e32 v109, v109
	v_mul_f32_e32 v106, 0xbfb8aa3b, v106
	v_mul_f32_e32 v107, 0xbfb8aa3b, v107
	v_exp_f32_e32 v106, v106
	v_exp_f32_e32 v107, v107
	s_nop 0
	v_pk_add_f32 v[110:111], v[106:107], 1.0 op_sel_hi:[1,0]
	v_rcp_f32_e32 v106, v108
	s_nop 0
	v_cvt_pk_bf16_f32 v106, v106, v109
	v_rcp_f32_e32 v107, v111
	v_pk_mul_f32 v[100:101], v[100:101], v[112:113] op_sel_hi:[1,0]
	v_mul_f32_e32 v100, 0xbfb8aa3b, v100
	v_mul_f32_e32 v101, 0xbfb8aa3b, v101
	v_exp_f32_e32 v100, v100
	v_exp_f32_e32 v101, v101
; DI unsigned pk2(float lo, float hi) { f32x2_t v = {lo, hi}; bf16x2_t b = __builtin_convertvector(v, bf16x2_t); return __builtin_bit_cast(unsigned, b); }
; DI float sigmoidf_(float x) { return 1.0f / (1.0f + __expf(-x)); }
;     DI void operator()(AccRef acc, const Unit& u, int wr, int wc, int fr, int fq) const {
;     ...
;                 const int row = row0 + ai * HALF + m * 16; const float rs = rsqrtf(SS0[row] * (1.0f / DM) + EPSN);
; #pragma unroll
;                 for (int bj = 0; bj < 2; ++bj) {
;                     const f32x4 v0 = acc[ai][bj][m][0] * rs, v1 = acc[ai][bj][m][1] * rs;
;                     u32x4 w; w.x = pk2(sigmoidf_(v0[0]), sigmoidf_(v0[1])); w.y = pk2(sigmoidf_(v0[2]), sigmoidf_(v0[3])); w.z = pk2(sigmoidf_(v1[0]), sigmoidf_(v1[1])); w.w = pk2(sigmoidf_(v1[2]), sigmoidf_(v1[3]));
;                     *(u32x4*)(D + (size_t)row * DM + col0 + bj * HALF) = w;
	v_rcp_f32_e32 v108, v110
	s_nop 0
	v_cvt_pk_bf16_f32 v107, v108, v107
	v_lshl_add_u64 v[108:109], s[80:81], 0, v[114:115]
	v_lshl_add_u64 v[108:109], v[108:109], 0, v[120:121]
	v_pk_add_f32 v[100:101], v[100:101], 1.0 op_sel_hi:[1,0]
	global_store_dwordx4 v[108:109], v[104:107], off
	v_pk_mul_f32 v[102:103], v[102:103], v[112:113] op_sel_hi:[1,0]
	v_pk_mul_f32 v[98:99], v[98:99], v[112:113] op_sel_hi:[1,0]
	v_pk_mul_f32 v[104:105], v[96:97], v[112:113] op_sel_hi:[1,0]
	v_mul_f32_e32 v98, 0xbfb8aa3b, v98
	v_mul_f32_e32 v99, 0xbfb8aa3b, v99
	v_rcp_f32_e32 v101, v101
	v_mul_f32_e32 v97, 0xbfb8aa3b, v103
	v_mul_f32_e32 v96, 0xbfb8aa3b, v102
	v_exp_f32_e32 v96, v96
	v_exp_f32_e32 v97, v97
	s_nop 0
	v_pk_add_f32 v[102:103], v[96:97], 1.0 op_sel_hi:[1,0]
	v_rcp_f32_e32 v96, v100
	s_nop 0
	v_cvt_pk_bf16_f32 v96, v96, v101
	v_mul_f32_e32 v101, 0xbfb8aa3b, v105
	v_mul_f32_e32 v100, 0xbfb8aa3b, v104
	v_exp_f32_e32 v100, v100
	v_exp_f32_e32 v101, v101
	v_rcp_f32_e32 v97, v103
	v_pk_add_f32 v[100:101], v[100:101], 1.0 op_sel_hi:[1,0]
	v_rcp_f32_e32 v102, v102
	s_nop 0
	v_cvt_pk_bf16_f32 v97, v102, v97
	v_rcp_f32_e32 v101, v101
	v_exp_f32_e32 v98, v98
	v_exp_f32_e32 v99, v99
	s_nop 0
	v_pk_add_f32 v[102:103], v[98:99], 1.0 op_sel_hi:[1,0]
	v_rcp_f32_e32 v98, v100
	s_nop 0
	v_cvt_pk_bf16_f32 v98, v98, v101
	v_rcp_f32_e32 v99, v103
	v_rcp_f32_e32 v100, v102
	s_nop 0
	v_cvt_pk_bf16_f32 v99, v100, v99
	global_store_dwordx4 v[108:109], v[96:99], off offset:256
	global_load_dword v96, v[156:157], off offset:128
	s_nop 0
	v_or_b32_e32 v98, 32, v158
	v_ashrrev_i32_e32 v99, 31, v98
	v_lshlrev_b64 v[98:99], 11, v[98:99]
	s_waitcnt vmcnt(0)
	v_fmamk_f32 v96, v96, 0x3a800000, v171
	v_mul_f32_e32 v97, 0x4b800000, v96
	v_cmp_gt_f32_e32 vcc, s60, v96
	s_nop 1
	v_cndmask_b32_e32 v96, v96, v97, vcc
	v_rsq_f32_e32 v96, v96
	s_nop 0
	v_mul_f32_e32 v97, 0x45800000, v96
	v_cndmask_b32_e32 v96, v96, v97, vcc
	v_pk_mul_f32 v[92:93], v[92:93], v[96:97] op_sel_hi:[1,0]
	s_nop 0
	v_mul_f32_e32 v92, 0xbfb8aa3b, v92
	v_mul_f32_e32 v93, 0xbfb8aa3b, v93
	v_exp_f32_e32 v92, v92
	v_exp_f32_e32 v93, v93
	s_nop 0
	v_pk_add_f32 v[92:93], v[92:93], 1.0 op_sel_hi:[1,0]
	s_nop 0
	v_pk_mul_f32 v[100:101], v[88:89], v[96:97] op_sel_hi:[1,0]
	v_pk_mul_f32 v[94:95], v[94:95], v[96:97] op_sel_hi:[1,0]
	v_pk_mul_f32 v[90:91], v[90:91], v[96:97] op_sel_hi:[1,0]
	v_rcp_f32_e32 v93, v93
	v_mul_f32_e32 v89, 0xbfb8aa3b, v95
	v_mul_f32_e32 v88, 0xbfb8aa3b, v94
	v_exp_f32_e32 v88, v88
	v_exp_f32_e32 v89, v89
	s_nop 0
	v_pk_add_f32 v[94:95], v[88:89], 1.0 op_sel_hi:[1,0]
	v_rcp_f32_e32 v88, v92
	s_nop 0
	v_cvt_pk_bf16_f32 v88, v88, v93
	v_mul_f32_e32 v93, 0xbfb8aa3b, v101
	v_mul_f32_e32 v92, 0xbfb8aa3b, v100
	v_exp_f32_e32 v92, v92
	v_exp_f32_e32 v93, v93
	v_rcp_f32_e32 v89, v95
	v_pk_add_f32 v[92:93], v[92:93], 1.0 op_sel_hi:[1,0]
	v_rcp_f32_e32 v94, v94
	s_nop 0
	v_cvt_pk_bf16_f32 v89, v94, v89
	v_rcp_f32_e32 v93, v93
	v_mul_f32_e32 v90, 0xbfb8aa3b, v90
	v_mul_f32_e32 v91, 0xbfb8aa3b, v91
	v_exp_f32_e32 v90, v90
	v_exp_f32_e32 v91, v91
	s_nop 0
	v_pk_add_f32 v[94:95], v[90:91], 1.0 op_sel_hi:[1,0]
	v_rcp_f32_e32 v90, v92
	s_nop 0
	v_cvt_pk_bf16_f32 v90, v90, v93
	v_rcp_f32_e32 v91, v95
	v_pk_mul_f32 v[84:85], v[84:85], v[96:97] op_sel_hi:[1,0]
	v_mul_f32_e32 v84, 0xbfb8aa3b, v84
	v_mul_f32_e32 v85, 0xbfb8aa3b, v85
	v_exp_f32_e32 v84, v84
	v_exp_f32_e32 v85, v85
	v_rcp_f32_e32 v92, v94
	s_nop 0
	v_cvt_pk_bf16_f32 v91, v92, v91
	v_lshl_add_u64 v[92:93], s[80:81], 0, v[98:99]
	v_lshl_add_u64 v[92:93], v[92:93], 0, v[120:121]
	v_pk_add_f32 v[84:85], v[84:85], 1.0 op_sel_hi:[1,0]
	global_store_dwordx4 v[92:93], v[88:91], off
	v_pk_mul_f32 v[86:87], v[86:87], v[96:97] op_sel_hi:[1,0]
	v_pk_mul_f32 v[82:83], v[82:83], v[96:97] op_sel_hi:[1,0]
	v_pk_mul_f32 v[88:89], v[80:81], v[96:97] op_sel_hi:[1,0]
	v_mul_f32_e32 v82, 0xbfb8aa3b, v82
	v_mul_f32_e32 v83, 0xbfb8aa3b, v83
	v_rcp_f32_e32 v85, v85
	v_mul_f32_e32 v81, 0xbfb8aa3b, v87
	v_mul_f32_e32 v80, 0xbfb8aa3b, v86
	v_exp_f32_e32 v80, v80
	v_exp_f32_e32 v81, v81
	s_nop 0
	v_pk_add_f32 v[86:87], v[80:81], 1.0 op_sel_hi:[1,0]
	v_rcp_f32_e32 v80, v84
	s_nop 0
	v_cvt_pk_bf16_f32 v80, v80, v85
	v_mul_f32_e32 v85, 0xbfb8aa3b, v89
	v_mul_f32_e32 v84, 0xbfb8aa3b, v88
	v_exp_f32_e32 v84, v84
	v_exp_f32_e32 v85, v85
	v_rcp_f32_e32 v81, v87
	v_pk_add_f32 v[84:85], v[84:85], 1.0 op_sel_hi:[1,0]
	v_rcp_f32_e32 v86, v86
	s_nop 0
	v_cvt_pk_bf16_f32 v81, v86, v81
	v_rcp_f32_e32 v85, v85
	v_exp_f32_e32 v82, v82
	v_exp_f32_e32 v83, v83
	s_nop 0
	v_pk_add_f32 v[86:87], v[82:83], 1.0 op_sel_hi:[1,0]
	v_rcp_f32_e32 v82, v84
	s_nop 0
	v_cvt_pk_bf16_f32 v82, v82, v85
	v_rcp_f32_e32 v83, v87
	v_rcp_f32_e32 v84, v86
	s_nop 0
	v_cvt_pk_bf16_f32 v83, v84, v83
	global_store_dwordx4 v[92:93], v[80:83], off offset:256
	global_load_dword v80, v[156:157], off offset:192
	s_nop 0
	v_or_b32_e32 v82, 48, v158
	v_ashrrev_i32_e32 v83, 31, v82
	v_lshlrev_b64 v[82:83], 11, v[82:83]
	s_waitcnt vmcnt(0)
; DI unsigned pk2(float lo, float hi) { f32x2_t v = {lo, hi}; bf16x2_t b = __builtin_convertvector(v, bf16x2_t); return __builtin_bit_cast(unsigned, b); }
; DI float sigmoidf_(float x) { return 1.0f / (1.0f + __expf(-x)); }
;     DI void operator()(AccRef acc, const Unit& u, int wr, int wc, int fr, int fq) const {
;     ...
;                 const int row = row0 + ai * HALF + m * 16; const float rs = rsqrtf(SS0[row] * (1.0f / DM) + EPSN);
; #pragma unroll
;                 for (int bj = 0; bj < 2; ++bj) {
;                     const f32x4 v0 = acc[ai][bj][m][0] * rs, v1 = acc[ai][bj][m][1] * rs;
;                     u32x4 w; w.x = pk2(sigmoidf_(v0[0]), sigmoidf_(v0[1])); w.y = pk2(sigmoidf_(v0[2]), sigmoidf_(v0[3])); w.z = pk2(sigmoidf_(v1[0]), sigmoidf_(v1[1])); w.w = pk2(sigmoidf_(v1[2]), sigmoidf_(v1[3]));
;                     *(u32x4*)(D + (size_t)row * DM + col0 + bj * HALF) = w;
	v_fmamk_f32 v80, v80, 0x3a800000, v171
	v_mul_f32_e32 v81, 0x4b800000, v80
	v_cmp_gt_f32_e32 vcc, s60, v80
	s_nop 1
	v_cndmask_b32_e32 v80, v80, v81, vcc
	v_rsq_f32_e32 v80, v80
	s_nop 0
	v_mul_f32_e32 v81, 0x45800000, v80
	v_cndmask_b32_e32 v80, v80, v81, vcc
	v_pk_mul_f32 v[76:77], v[76:77], v[80:81] op_sel_hi:[1,0]
	s_nop 0
	v_mul_f32_e32 v76, 0xbfb8aa3b, v76
	v_mul_f32_e32 v77, 0xbfb8aa3b, v77
	v_exp_f32_e32 v76, v76
	v_exp_f32_e32 v77, v77
	s_nop 0
	v_pk_add_f32 v[76:77], v[76:77], 1.0 op_sel_hi:[1,0]
	s_nop 0
	v_pk_mul_f32 v[84:85], v[72:73], v[80:81] op_sel_hi:[1,0]
	v_pk_mul_f32 v[78:79], v[78:79], v[80:81] op_sel_hi:[1,0]
	v_pk_mul_f32 v[74:75], v[74:75], v[80:81] op_sel_hi:[1,0]
	v_rcp_f32_e32 v77, v77
	v_mul_f32_e32 v73, 0xbfb8aa3b, v79
	v_mul_f32_e32 v72, 0xbfb8aa3b, v78
	v_exp_f32_e32 v72, v72
	v_exp_f32_e32 v73, v73
	s_nop 0
	v_pk_add_f32 v[78:79], v[72:73], 1.0 op_sel_hi:[1,0]
	v_rcp_f32_e32 v72, v76
	s_nop 0
	v_cvt_pk_bf16_f32 v72, v72, v77
	v_mul_f32_e32 v77, 0xbfb8aa3b, v85
	v_mul_f32_e32 v76, 0xbfb8aa3b, v84
	v_exp_f32_e32 v76, v76
	v_exp_f32_e32 v77, v77
	v_rcp_f32_e32 v73, v79
	v_pk_add_f32 v[76:77], v[76:77], 1.0 op_sel_hi:[1,0]
	v_rcp_f32_e32 v78, v78
	s_nop 0
	v_cvt_pk_bf16_f32 v73, v78, v73
	v_rcp_f32_e32 v77, v77
	v_mul_f32_e32 v74, 0xbfb8aa3b, v74
	v_mul_f32_e32 v75, 0xbfb8aa3b, v75
	v_exp_f32_e32 v74, v74
	v_exp_f32_e32 v75, v75
	s_nop 0
	v_pk_add_f32 v[78:79], v[74:75], 1.0 op_sel_hi:[1,0]
	v_rcp_f32_e32 v74, v76
	s_nop 0
	v_cvt_pk_bf16_f32 v74, v74, v77
	v_rcp_f32_e32 v75, v79
	v_pk_mul_f32 v[68:69], v[68:69], v[80:81] op_sel_hi:[1,0]
	v_mul_f32_e32 v68, 0xbfb8aa3b, v68
	v_mul_f32_e32 v69, 0xbfb8aa3b, v69
	v_exp_f32_e32 v68, v68
	v_exp_f32_e32 v69, v69
	v_rcp_f32_e32 v76, v78
	s_nop 0
	v_cvt_pk_bf16_f32 v75, v76, v75
	v_lshl_add_u64 v[76:77], s[80:81], 0, v[82:83]
	v_lshl_add_u64 v[76:77], v[76:77], 0, v[120:121]
	v_pk_add_f32 v[68:69], v[68:69], 1.0 op_sel_hi:[1,0]
	global_store_dwordx4 v[76:77], v[72:75], off
	v_pk_mul_f32 v[70:71], v[70:71], v[80:81] op_sel_hi:[1,0]
	v_pk_mul_f32 v[66:67], v[66:67], v[80:81] op_sel_hi:[1,0]
	v_pk_mul_f32 v[72:73], v[64:65], v[80:81] op_sel_hi:[1,0]
	v_mul_f32_e32 v66, 0xbfb8aa3b, v66
	v_mul_f32_e32 v67, 0xbfb8aa3b, v67
	v_rcp_f32_e32 v69, v69
	v_mul_f32_e32 v65, 0xbfb8aa3b, v71
	v_mul_f32_e32 v64, 0xbfb8aa3b, v70
	v_exp_f32_e32 v64, v64
	v_exp_f32_e32 v65, v65
	s_nop 0
	v_pk_add_f32 v[70:71], v[64:65], 1.0 op_sel_hi:[1,0]
	v_rcp_f32_e32 v64, v68
	s_nop 0
	v_cvt_pk_bf16_f32 v64, v64, v69
	v_mul_f32_e32 v69, 0xbfb8aa3b, v73
	v_mul_f32_e32 v68, 0xbfb8aa3b, v72
	v_exp_f32_e32 v68, v68
	v_exp_f32_e32 v69, v69
	v_rcp_f32_e32 v65, v71
	v_pk_add_f32 v[68:69], v[68:69], 1.0 op_sel_hi:[1,0]
	v_rcp_f32_e32 v70, v70
	s_nop 0
	v_cvt_pk_bf16_f32 v65, v70, v65
	v_rcp_f32_e32 v69, v69
	v_exp_f32_e32 v66, v66
	v_exp_f32_e32 v67, v67
	s_nop 0
	v_pk_add_f32 v[70:71], v[66:67], 1.0 op_sel_hi:[1,0]
	v_rcp_f32_e32 v66, v68
	s_nop 0
	v_cvt_pk_bf16_f32 v66, v66, v69
	v_rcp_f32_e32 v67, v71
	v_rcp_f32_e32 v68, v70
	s_nop 0
	v_cvt_pk_bf16_f32 v67, v68, v67
	global_store_dwordx4 v[76:77], v[64:67], off offset:256
	global_load_dword v64, v[156:157], off offset:512
	s_waitcnt vmcnt(0)
	v_fmamk_f32 v64, v64, 0x3a800000, v171
	v_mul_f32_e32 v65, 0x4b800000, v64
	v_cmp_gt_f32_e32 vcc, s60, v64
	s_nop 1
	v_cndmask_b32_e32 v64, v64, v65, vcc
	v_rsq_f32_e32 v64, v64
	s_nop 0
	v_mul_f32_e32 v65, 0x45800000, v64
	v_cndmask_b32_e32 v64, v64, v65, vcc
	v_pk_mul_f32 v[60:61], v[60:61], v[64:65] op_sel_hi:[1,0]
	s_nop 0
	v_mul_f32_e32 v60, 0xbfb8aa3b, v60
	v_mul_f32_e32 v61, 0xbfb8aa3b, v61
	v_exp_f32_e32 v60, v60
	v_exp_f32_e32 v61, v61
	s_nop 0
	v_pk_add_f32 v[60:61], v[60:61], 1.0 op_sel_hi:[1,0]
	s_nop 0
	v_pk_mul_f32 v[66:67], v[56:57], v[64:65] op_sel_hi:[1,0]
	v_pk_mul_f32 v[62:63], v[62:63], v[64:65] op_sel_hi:[1,0]
	v_pk_mul_f32 v[58:59], v[58:59], v[64:65] op_sel_hi:[1,0]
	v_rcp_f32_e32 v61, v61
	v_mul_f32_e32 v57, 0xbfb8aa3b, v63
	v_mul_f32_e32 v56, 0xbfb8aa3b, v62
	v_exp_f32_e32 v56, v56
	v_exp_f32_e32 v57, v57
	s_nop 0
	v_pk_add_f32 v[62:63], v[56:57], 1.0 op_sel_hi:[1,0]
	v_rcp_f32_e32 v56, v60
	s_nop 0
	v_cvt_pk_bf16_f32 v56, v56, v61
	v_mul_f32_e32 v61, 0xbfb8aa3b, v67
	v_mul_f32_e32 v60, 0xbfb8aa3b, v66
	v_exp_f32_e32 v60, v60
	v_exp_f32_e32 v61, v61
	v_rcp_f32_e32 v57, v63
	v_pk_add_f32 v[60:61], v[60:61], 1.0 op_sel_hi:[1,0]
	v_rcp_f32_e32 v62, v62
	s_nop 0
	v_cvt_pk_bf16_f32 v57, v62, v57
	v_rcp_f32_e32 v61, v61
	v_mul_f32_e32 v58, 0xbfb8aa3b, v58
	v_mul_f32_e32 v59, 0xbfb8aa3b, v59
	v_exp_f32_e32 v58, v58
	v_exp_f32_e32 v59, v59
	s_nop 0
	v_pk_add_f32 v[62:63], v[58:59], 1.0 op_sel_hi:[1,0]
	v_rcp_f32_e32 v58, v60
	s_nop 0
	v_cvt_pk_bf16_f32 v58, v58, v61
	v_rcp_f32_e32 v59, v63
	s_mov_b64 s[0:1], 0x40000
	v_pk_mul_f32 v[52:53], v[52:53], v[64:65] op_sel_hi:[1,0]
	v_mul_f32_e32 v52, 0xbfb8aa3b, v52
	v_mul_f32_e32 v53, 0xbfb8aa3b, v53
	v_exp_f32_e32 v52, v52
	v_exp_f32_e32 v53, v53
	v_rcp_f32_e32 v60, v62
	s_nop 0
	v_cvt_pk_bf16_f32 v59, v60, v59
	v_lshl_add_u64 v[60:61], v[116:117], 0, s[0:1]
	s_mov_b32 s0, 0x40000
	v_add_co_u32_e32 v62, vcc, s0, v116
	v_pk_add_f32 v[52:53], v[52:53], 1.0 op_sel_hi:[1,0]
	s_nop 0
	v_addc_co_u32_e32 v63, vcc, 0, v117, vcc
	global_store_dwordx4 v[62:63], v[56:59], off
	v_pk_mul_f32 v[54:55], v[54:55], v[64:65] op_sel_hi:[1,0]
	v_pk_mul_f32 v[50:51], v[50:51], v[64:65] op_sel_hi:[1,0]
	v_pk_mul_f32 v[56:57], v[48:49], v[64:65] op_sel_hi:[1,0]
	v_mul_f32_e32 v50, 0xbfb8aa3b, v50
	v_mul_f32_e32 v51, 0xbfb8aa3b, v51
	v_rcp_f32_e32 v53, v53
	v_mul_f32_e32 v49, 0xbfb8aa3b, v55
	v_mul_f32_e32 v48, 0xbfb8aa3b, v54
	v_exp_f32_e32 v48, v48
	v_exp_f32_e32 v49, v49
	s_nop 0
	v_pk_add_f32 v[54:55], v[48:49], 1.0 op_sel_hi:[1,0]
	v_rcp_f32_e32 v48, v52
	s_nop 0
	v_cvt_pk_bf16_f32 v48, v48, v53
	v_mul_f32_e32 v53, 0xbfb8aa3b, v57
	v_mul_f32_e32 v52, 0xbfb8aa3b, v56
	v_exp_f32_e32 v52, v52
	v_exp_f32_e32 v53, v53
	v_rcp_f32_e32 v49, v55
	v_pk_add_f32 v[52:53], v[52:53], 1.0 op_sel_hi:[1,0]
	v_rcp_f32_e32 v54, v54
	s_nop 0
	v_cvt_pk_bf16_f32 v49, v54, v49
	v_rcp_f32_e32 v53, v53
	v_exp_f32_e32 v50, v50
	v_exp_f32_e32 v51, v51
	s_nop 0
	v_pk_add_f32 v[54:55], v[50:51], 1.0 op_sel_hi:[1,0]
	v_rcp_f32_e32 v50, v52
	s_nop 0
	v_cvt_pk_bf16_f32 v50, v50, v53
	v_rcp_f32_e32 v51, v55
	v_rcp_f32_e32 v52, v54
	s_nop 0
	v_cvt_pk_bf16_f32 v51, v52, v51
	global_store_dwordx4 v[60:61], v[48:51], off offset:256
	global_load_dword v48, v[156:157], off offset:576
	s_waitcnt vmcnt(0)
; DI unsigned pk2(float lo, float hi) { f32x2_t v = {lo, hi}; bf16x2_t b = __builtin_convertvector(v, bf16x2_t); return __builtin_bit_cast(unsigned, b); }
; DI float sigmoidf_(float x) { return 1.0f / (1.0f + __expf(-x)); }
;     DI void operator()(AccRef acc, const Unit& u, int wr, int wc, int fr, int fq) const {
;     ...
;                 const int row = row0 + ai * HALF + m * 16; const float rs = rsqrtf(SS0[row] * (1.0f / DM) + EPSN);
; #pragma unroll
;                 for (int bj = 0; bj < 2; ++bj) {
;                     const f32x4 v0 = acc[ai][bj][m][0] * rs, v1 = acc[ai][bj][m][1] * rs;
;                     u32x4 w; w.x = pk2(sigmoidf_(v0[0]), sigmoidf_(v0[1])); w.y = pk2(sigmoidf_(v0[2]), sigmoidf_(v0[3])); w.z = pk2(sigmoidf_(v1[0]), sigmoidf_(v1[1])); w.w = pk2(sigmoidf_(v1[2]), sigmoidf_(v1[3]));
;                     *(u32x4*)(D + (size_t)row * DM + col0 + bj * HALF) = w;
	v_fmamk_f32 v48, v48, 0x3a800000, v171
	v_mul_f32_e32 v49, 0x4b800000, v48
	v_cmp_gt_f32_e32 vcc, s60, v48
	s_nop 1
	v_cndmask_b32_e32 v48, v48, v49, vcc
	v_rsq_f32_e32 v48, v48
	s_nop 0
	v_mul_f32_e32 v49, 0x45800000, v48
	v_cndmask_b32_e32 v48, v48, v49, vcc
	v_pk_mul_f32 v[44:45], v[44:45], v[48:49] op_sel_hi:[1,0]
	s_nop 0
	v_mul_f32_e32 v44, 0xbfb8aa3b, v44
	v_mul_f32_e32 v45, 0xbfb8aa3b, v45
	v_exp_f32_e32 v44, v44
	v_exp_f32_e32 v45, v45
	s_nop 0
	v_pk_add_f32 v[44:45], v[44:45], 1.0 op_sel_hi:[1,0]
	s_nop 0
	v_pk_mul_f32 v[50:51], v[40:41], v[48:49] op_sel_hi:[1,0]
	v_pk_mul_f32 v[46:47], v[46:47], v[48:49] op_sel_hi:[1,0]
	v_pk_mul_f32 v[42:43], v[42:43], v[48:49] op_sel_hi:[1,0]
	v_rcp_f32_e32 v45, v45
	v_mul_f32_e32 v41, 0xbfb8aa3b, v47
	v_mul_f32_e32 v40, 0xbfb8aa3b, v46
	v_exp_f32_e32 v40, v40
	v_exp_f32_e32 v41, v41
	s_nop 0
	v_pk_add_f32 v[46:47], v[40:41], 1.0 op_sel_hi:[1,0]
	v_rcp_f32_e32 v40, v44
	s_nop 0
	v_cvt_pk_bf16_f32 v40, v40, v45
	v_mul_f32_e32 v45, 0xbfb8aa3b, v51
	v_mul_f32_e32 v44, 0xbfb8aa3b, v50
	v_exp_f32_e32 v44, v44
	v_exp_f32_e32 v45, v45
	v_rcp_f32_e32 v41, v47
	v_pk_add_f32 v[44:45], v[44:45], 1.0 op_sel_hi:[1,0]
	v_rcp_f32_e32 v46, v46
	s_nop 0
	v_cvt_pk_bf16_f32 v41, v46, v41
	v_rcp_f32_e32 v45, v45
	v_mul_f32_e32 v42, 0xbfb8aa3b, v42
	v_mul_f32_e32 v43, 0xbfb8aa3b, v43
	v_exp_f32_e32 v42, v42
	v_exp_f32_e32 v43, v43
	s_nop 0
	v_pk_add_f32 v[46:47], v[42:43], 1.0 op_sel_hi:[1,0]
	v_rcp_f32_e32 v42, v44
	s_nop 0
	v_cvt_pk_bf16_f32 v42, v42, v45
	v_rcp_f32_e32 v43, v47
	s_mov_b64 s[0:1], 0x48000
	v_pk_mul_f32 v[36:37], v[36:37], v[48:49] op_sel_hi:[1,0]
	v_mul_f32_e32 v36, 0xbfb8aa3b, v36
	v_mul_f32_e32 v37, 0xbfb8aa3b, v37
	v_exp_f32_e32 v36, v36
	v_exp_f32_e32 v37, v37
	v_rcp_f32_e32 v44, v46
	v_add_co_u32_e32 v46, vcc, s61, v116
	v_cvt_pk_bf16_f32 v43, v44, v43
	s_nop 0
	v_addc_co_u32_e32 v47, vcc, 0, v117, vcc
	v_pk_add_f32 v[36:37], v[36:37], 1.0 op_sel_hi:[1,0]
	v_lshl_add_u64 v[44:45], v[116:117], 0, s[0:1]
	global_store_dwordx4 v[46:47], v[40:43], off
	v_pk_mul_f32 v[38:39], v[38:39], v[48:49] op_sel_hi:[1,0]
	v_pk_mul_f32 v[34:35], v[34:35], v[48:49] op_sel_hi:[1,0]
	v_pk_mul_f32 v[40:41], v[32:33], v[48:49] op_sel_hi:[1,0]
	v_mul_f32_e32 v34, 0xbfb8aa3b, v34
	v_mul_f32_e32 v35, 0xbfb8aa3b, v35
	v_rcp_f32_e32 v37, v37
	v_mul_f32_e32 v33, 0xbfb8aa3b, v39
	v_mul_f32_e32 v32, 0xbfb8aa3b, v38
	v_exp_f32_e32 v32, v32
	v_exp_f32_e32 v33, v33
	s_nop 0
	v_pk_add_f32 v[38:39], v[32:33], 1.0 op_sel_hi:[1,0]
	v_rcp_f32_e32 v32, v36
	s_nop 0
	v_cvt_pk_bf16_f32 v32, v32, v37
	v_mul_f32_e32 v37, 0xbfb8aa3b, v41
	v_mul_f32_e32 v36, 0xbfb8aa3b, v40
	v_exp_f32_e32 v36, v36
	v_exp_f32_e32 v37, v37
	v_rcp_f32_e32 v33, v39
	v_pk_add_f32 v[36:37], v[36:37], 1.0 op_sel_hi:[1,0]
	v_rcp_f32_e32 v38, v38
	s_nop 0
	v_cvt_pk_bf16_f32 v33, v38, v33
	v_rcp_f32_e32 v37, v37
	v_exp_f32_e32 v34, v34
	v_exp_f32_e32 v35, v35
	s_nop 0
	v_pk_add_f32 v[38:39], v[34:35], 1.0 op_sel_hi:[1,0]
	v_rcp_f32_e32 v34, v36
	s_nop 0
	v_cvt_pk_bf16_f32 v34, v34, v37
	v_rcp_f32_e32 v35, v39
	v_rcp_f32_e32 v36, v38
	s_nop 0
	v_cvt_pk_bf16_f32 v35, v36, v35
	global_store_dwordx4 v[44:45], v[32:35], off offset:256
	global_load_dword v32, v[156:157], off offset:640
	s_waitcnt vmcnt(0)
; DI unsigned pk2(float lo, float hi) { f32x2_t v = {lo, hi}; bf16x2_t b = __builtin_convertvector(v, bf16x2_t); return __builtin_bit_cast(unsigned, b); }
; DI float sigmoidf_(float x) { return 1.0f / (1.0f + __expf(-x)); }
;     DI void operator()(AccRef acc, const Unit& u, int wr, int wc, int fr, int fq) const {
;     ...
;                 const int row = row0 + ai * HALF + m * 16; const float rs = rsqrtf(SS0[row] * (1.0f / DM) + EPSN);
; #pragma unroll
;                 for (int bj = 0; bj < 2; ++bj) {
;                     const f32x4 v0 = acc[ai][bj][m][0] * rs, v1 = acc[ai][bj][m][1] * rs;
;                     u32x4 w; w.x = pk2(sigmoidf_(v0[0]), sigmoidf_(v0[1])); w.y = pk2(sigmoidf_(v0[2]), sigmoidf_(v0[3])); w.z = pk2(sigmoidf_(v1[0]), sigmoidf_(v1[1])); w.w = pk2(sigmoidf_(v1[2]), sigmoidf_(v1[3]));
;                     *(u32x4*)(D + (size_t)row * DM + col0 + bj * HALF) = w;
	v_fmamk_f32 v32, v32, 0x3a800000, v171
	v_mul_f32_e32 v33, 0x4b800000, v32
	v_cmp_gt_f32_e32 vcc, s60, v32
	s_nop 1
	v_cndmask_b32_e32 v32, v32, v33, vcc
	v_rsq_f32_e32 v32, v32
	s_nop 0
	v_mul_f32_e32 v33, 0x45800000, v32
	v_cndmask_b32_e32 v32, v32, v33, vcc
	v_pk_mul_f32 v[28:29], v[28:29], v[32:33] op_sel_hi:[1,0]
	s_nop 0
	v_mul_f32_e32 v28, 0xbfb8aa3b, v28
	v_mul_f32_e32 v29, 0xbfb8aa3b, v29
	v_exp_f32_e32 v28, v28
	v_exp_f32_e32 v29, v29
	s_nop 0
	v_pk_add_f32 v[28:29], v[28:29], 1.0 op_sel_hi:[1,0]
	s_nop 0
	v_pk_mul_f32 v[34:35], v[24:25], v[32:33] op_sel_hi:[1,0]
	v_pk_mul_f32 v[30:31], v[30:31], v[32:33] op_sel_hi:[1,0]
	v_pk_mul_f32 v[26:27], v[26:27], v[32:33] op_sel_hi:[1,0]
	v_rcp_f32_e32 v29, v29
	v_mul_f32_e32 v25, 0xbfb8aa3b, v31
	v_mul_f32_e32 v24, 0xbfb8aa3b, v30
	v_exp_f32_e32 v24, v24
	v_exp_f32_e32 v25, v25
	s_nop 0
	v_pk_add_f32 v[30:31], v[24:25], 1.0 op_sel_hi:[1,0]
	v_rcp_f32_e32 v24, v28
	s_nop 0
	v_cvt_pk_bf16_f32 v24, v24, v29
	v_mul_f32_e32 v29, 0xbfb8aa3b, v35
	v_mul_f32_e32 v28, 0xbfb8aa3b, v34
	v_exp_f32_e32 v28, v28
	v_exp_f32_e32 v29, v29
	v_rcp_f32_e32 v25, v31
	v_pk_add_f32 v[28:29], v[28:29], 1.0 op_sel_hi:[1,0]
	v_rcp_f32_e32 v30, v30
	s_nop 0
	v_cvt_pk_bf16_f32 v25, v30, v25
	v_rcp_f32_e32 v29, v29
	v_mul_f32_e32 v26, 0xbfb8aa3b, v26
	v_mul_f32_e32 v27, 0xbfb8aa3b, v27
	v_exp_f32_e32 v26, v26
	v_exp_f32_e32 v27, v27
	s_nop 0
	v_pk_add_f32 v[30:31], v[26:27], 1.0 op_sel_hi:[1,0]
	v_rcp_f32_e32 v26, v28
	s_nop 0
	v_cvt_pk_bf16_f32 v26, v26, v29
	v_rcp_f32_e32 v27, v31
	v_pk_mul_f32 v[20:21], v[20:21], v[32:33] op_sel_hi:[1,0]
	v_mul_f32_e32 v20, 0xbfb8aa3b, v20
	v_mul_f32_e32 v21, 0xbfb8aa3b, v21
	v_exp_f32_e32 v20, v20
	v_exp_f32_e32 v21, v21
	v_rcp_f32_e32 v28, v30
	v_add_co_u32_e32 v30, vcc, s62, v116
	v_cvt_pk_bf16_f32 v27, v28, v27
	s_nop 0
	v_addc_co_u32_e32 v31, vcc, 0, v117, vcc
	v_pk_add_f32 v[20:21], v[20:21], 1.0 op_sel_hi:[1,0]
	global_store_dwordx4 v[30:31], v[24:27], off
	v_pk_mul_f32 v[22:23], v[22:23], v[32:33] op_sel_hi:[1,0]
	v_pk_mul_f32 v[18:19], v[18:19], v[32:33] op_sel_hi:[1,0]
	v_pk_mul_f32 v[24:25], v[16:17], v[32:33] op_sel_hi:[1,0]
	v_mul_f32_e32 v18, 0xbfb8aa3b, v18
	v_mul_f32_e32 v19, 0xbfb8aa3b, v19
	v_rcp_f32_e32 v21, v21
	v_mul_f32_e32 v17, 0xbfb8aa3b, v23
	v_mul_f32_e32 v16, 0xbfb8aa3b, v22
	v_exp_f32_e32 v16, v16
	v_exp_f32_e32 v17, v17
	s_nop 0
	v_pk_add_f32 v[22:23], v[16:17], 1.0 op_sel_hi:[1,0]
	v_rcp_f32_e32 v16, v20
	s_nop 0
	v_cvt_pk_bf16_f32 v16, v16, v21
	v_mul_f32_e32 v21, 0xbfb8aa3b, v25
	v_mul_f32_e32 v20, 0xbfb8aa3b, v24
	v_exp_f32_e32 v20, v20
	v_exp_f32_e32 v21, v21
	v_rcp_f32_e32 v17, v23
	v_pk_add_f32 v[20:21], v[20:21], 1.0 op_sel_hi:[1,0]
	v_rcp_f32_e32 v22, v22
	s_nop 0
	v_cvt_pk_bf16_f32 v17, v22, v17
	v_rcp_f32_e32 v21, v21
	v_exp_f32_e32 v18, v18
	v_exp_f32_e32 v19, v19
	s_nop 0
	v_pk_add_f32 v[22:23], v[18:19], 1.0 op_sel_hi:[1,0]
	v_rcp_f32_e32 v18, v20
	s_nop 0
	v_cvt_pk_bf16_f32 v18, v18, v21
	v_lshl_add_u64 v[28:29], v[116:117], 0, s[22:23]
	v_rcp_f32_e32 v19, v23
	v_rcp_f32_e32 v20, v22
	s_nop 0
	v_cvt_pk_bf16_f32 v19, v20, v19
	global_store_dwordx4 v[28:29], v[16:19], off offset:256
	global_load_dword v16, v[156:157], off offset:704
	s_waitcnt vmcnt(0)
	v_fmamk_f32 v16, v16, 0x3a800000, v171
	v_mul_f32_e32 v17, 0x4b800000, v16
	v_cmp_gt_f32_e32 vcc, s60, v16
	s_nop 1
	v_cndmask_b32_e32 v16, v16, v17, vcc
	v_rsq_f32_e32 v16, v16
	s_nop 0
	v_mul_f32_e32 v17, 0x45800000, v16
	v_cndmask_b32_e32 v16, v16, v17, vcc
	v_pk_mul_f32 v[12:13], v[12:13], v[16:17] op_sel_hi:[1,0]
	s_nop 0
	v_mul_f32_e32 v12, 0xbfb8aa3b, v12
	v_mul_f32_e32 v13, 0xbfb8aa3b, v13
	v_exp_f32_e32 v12, v12
	v_exp_f32_e32 v13, v13
	s_nop 0
	v_pk_add_f32 v[12:13], v[12:13], 1.0 op_sel_hi:[1,0]
	s_nop 0
	v_pk_mul_f32 v[18:19], v[8:9], v[16:17] op_sel_hi:[1,0]
	v_pk_mul_f32 v[14:15], v[14:15], v[16:17] op_sel_hi:[1,0]
	v_pk_mul_f32 v[10:11], v[10:11], v[16:17] op_sel_hi:[1,0]
	v_rcp_f32_e32 v13, v13
	v_mul_f32_e32 v9, 0xbfb8aa3b, v15
	v_mul_f32_e32 v8, 0xbfb8aa3b, v14
	v_exp_f32_e32 v8, v8
	v_exp_f32_e32 v9, v9
	s_nop 0
	v_pk_add_f32 v[14:15], v[8:9], 1.0 op_sel_hi:[1,0]
	v_rcp_f32_e32 v8, v12
	s_nop 0
	v_cvt_pk_bf16_f32 v8, v8, v13
	v_mul_f32_e32 v13, 0xbfb8aa3b, v19
	v_mul_f32_e32 v12, 0xbfb8aa3b, v18
	v_exp_f32_e32 v12, v12
	v_exp_f32_e32 v13, v13
	v_rcp_f32_e32 v9, v15
	v_pk_add_f32 v[12:13], v[12:13], 1.0 op_sel_hi:[1,0]
	v_rcp_f32_e32 v14, v14
	s_nop 0
	v_cvt_pk_bf16_f32 v9, v14, v9
	v_rcp_f32_e32 v13, v13
	v_mul_f32_e32 v10, 0xbfb8aa3b, v10
	v_mul_f32_e32 v11, 0xbfb8aa3b, v11
	v_exp_f32_e32 v10, v10
	v_exp_f32_e32 v11, v11
	s_nop 0
	v_pk_add_f32 v[14:15], v[10:11], 1.0 op_sel_hi:[1,0]
	v_rcp_f32_e32 v10, v12
	s_nop 0
	v_cvt_pk_bf16_f32 v10, v10, v13
	v_rcp_f32_e32 v11, v15
	v_pk_mul_f32 v[4:5], v[4:5], v[16:17] op_sel_hi:[1,0]
	v_mul_f32_e32 v4, 0xbfb8aa3b, v4
	v_mul_f32_e32 v5, 0xbfb8aa3b, v5
	v_exp_f32_e32 v4, v4
	v_exp_f32_e32 v5, v5
	v_rcp_f32_e32 v12, v14
	v_add_co_u32_e32 v14, vcc, s63, v116
	v_cvt_pk_bf16_f32 v11, v12, v11
	s_nop 0
	v_addc_co_u32_e32 v15, vcc, 0, v117, vcc
	v_pk_add_f32 v[4:5], v[4:5], 1.0 op_sel_hi:[1,0]
	global_store_dwordx4 v[14:15], v[8:11], off
	v_pk_mul_f32 v[6:7], v[6:7], v[16:17] op_sel_hi:[1,0]
	v_pk_mul_f32 v[2:3], v[2:3], v[16:17] op_sel_hi:[1,0]
	v_pk_mul_f32 v[8:9], v[0:1], v[16:17] op_sel_hi:[1,0]
	v_mul_f32_e32 v2, 0xbfb8aa3b, v2
	v_mul_f32_e32 v3, 0xbfb8aa3b, v3
	v_rcp_f32_e32 v5, v5
	v_mul_f32_e32 v1, 0xbfb8aa3b, v7
	v_mul_f32_e32 v0, 0xbfb8aa3b, v6
	v_exp_f32_e32 v0, v0
	v_exp_f32_e32 v1, v1
	s_nop 0
	v_pk_add_f32 v[6:7], v[0:1], 1.0 op_sel_hi:[1,0]
	v_rcp_f32_e32 v0, v4
	s_nop 0
	v_cvt_pk_bf16_f32 v0, v0, v5
	v_mul_f32_e32 v5, 0xbfb8aa3b, v9
	v_mul_f32_e32 v4, 0xbfb8aa3b, v8
	v_exp_f32_e32 v4, v4
	v_exp_f32_e32 v5, v5
	v_rcp_f32_e32 v1, v7
	v_pk_add_f32 v[4:5], v[4:5], 1.0 op_sel_hi:[1,0]
	v_rcp_f32_e32 v6, v6
	s_nop 0
	v_cvt_pk_bf16_f32 v1, v6, v1
	v_rcp_f32_e32 v5, v5
	v_exp_f32_e32 v2, v2
	v_exp_f32_e32 v3, v3
	s_nop 0
	v_pk_add_f32 v[6:7], v[2:3], 1.0 op_sel_hi:[1,0]
	v_rcp_f32_e32 v2, v4
	s_nop 0
	v_cvt_pk_bf16_f32 v2, v2, v5
	v_lshl_add_u64 v[12:13], v[116:117], 0, s[24:25]
	v_rcp_f32_e32 v3, v7
	s_mov_b64 s[0:1], -1
	v_rcp_f32_e32 v4, v6
	s_nop 0
	v_cvt_pk_bf16_f32 v3, v4, v3
	s_andn2_b64 vcc, exec, s[4:5]
	global_store_dwordx4 v[12:13], v[0:3], off offset:256
	s_cbranch_vccnz .LBB0_1287
	s_andn2_b64 vcc, exec, s[16:17]
	s_cbranch_vccnz .LBB0_1286
	s_barrier
	s_branch .LBB0_1286

; DI unsigned pk2(float lo, float hi) { f32x2_t v = {lo, hi}; bf16x2_t b = __builtin_convertvector(v, bf16x2_t); return __builtin_bit_cast(unsigned, b); }
; DI float sigmoidf_(float x) { return 1.0f / (1.0f + __expf(-x)); }
;     DI void operator()(AccRef acc, const Unit& u, int wr, int wc, int fr, int fq) const {
;     ...
;                 const int row = row0 + ai * HALF + m * 16; const float rs = rsqrtf(SS1[row] * (1.0f / DM) + EPSN);
;                 float h[8];
; #pragma unroll
;                 for (int n = 0; n < 2; ++n)
; #pragma unroll
;                     for (int e = 0; e < 4; ++e) { const float g = acc[ai][0][m][n][e] * rs, up = acc[ai][1][m][n][e] * rs; h[4 * n + e] = g * sigmoidf_(g) * up; }
;                 u32x4 w; w.x = pk2(h[0], h[1]); w.y = pk2(h[2], h[3]); w.z = pk2(h[4], h[5]); w.w = pk2(h[6], h[7]);
;                 *(u32x4*)(H + (size_t)row * DFF + col0) = w;
.LBB0_1490:
	v_lshl_add_u32 v144, s0, 8, v149
	v_ashrrev_i32_e32 v145, 31, v144
	v_lshl_add_u64 v[146:147], v[144:145], 2, s[46:47]
	global_load_dword v145, v[146:147], off
	s_waitcnt vmcnt(0)
	v_fmamk_f32 v145, v145, 0x3a800000, v158
	v_mul_f32_e32 v152, 0x4b800000, v145
	v_cmp_gt_f32_e32 vcc, s43, v145
	s_nop 1
	v_cndmask_b32_e32 v145, v145, v152, vcc
	v_rsq_f32_e32 v145, v145
	v_lshl_or_b32 v152, s1, 7, v154
	v_ashrrev_i32_e32 v153, 31, v152
	v_mul_f32_e32 v159, 0x45800000, v145
	v_cndmask_b32_e32 v160, v145, v159, vcc
	v_pk_mul_f32 v[124:125], v[124:125], v[160:161] op_sel_hi:[1,0]
	v_pk_mul_f32 v[126:127], v[126:127], v[160:161] op_sel_hi:[1,0]
	v_mul_f32_e32 v145, 0xbfb8aa3b, v124
	v_mul_f32_e32 v159, 0xbfb8aa3b, v125
	v_exp_f32_e32 v162, v145
	v_exp_f32_e32 v163, v159
	v_pk_mul_f32 v[120:121], v[120:121], v[160:161] op_sel_hi:[1,0]
	v_pk_mul_f32 v[122:123], v[122:123], v[160:161] op_sel_hi:[1,0]
	v_pk_mul_f32 v[116:117], v[116:117], v[160:161] op_sel_hi:[1,0]
	v_mul_f32_e32 v161, 0xbfb8aa3b, v126
	v_mul_f32_e32 v165, 0xbfb8aa3b, v127
	v_exp_f32_e32 v164, v161
	v_exp_f32_e32 v165, v165
	v_pk_add_f32 v[162:163], v[162:163], 1.0 op_sel_hi:[1,0]
	v_pk_mul_f32 v[112:113], v[112:113], v[160:161] op_sel_hi:[1,0]
	v_pk_add_f32 v[164:165], v[164:165], 1.0 op_sel_hi:[1,0]
	v_mul_f32_e32 v166, 0xbfb8aa3b, v116
	v_mul_f32_e32 v167, 0xbfb8aa3b, v117
	v_exp_f32_e32 v166, v166
	v_exp_f32_e32 v167, v167
	s_nop 0
	v_pk_add_f32 v[166:167], v[166:167], 1.0 op_sel_hi:[1,0]
	v_rcp_f32_e32 v163, v163
	v_rcp_f32_e32 v162, v162
	s_nop 0
	v_pk_mul_f32 v[124:125], v[124:125], v[162:163]
	v_rcp_f32_e32 v163, v165
	v_rcp_f32_e32 v162, v164
	v_pk_mul_f32 v[120:121], v[120:121], v[124:125]
	v_pk_mul_f32 v[124:125], v[126:127], v[162:163]
	v_pk_mul_f32 v[118:119], v[118:119], v[160:161] op_sel_hi:[1,0]
	v_pk_mul_f32 v[122:123], v[122:123], v[124:125]
	v_mul_f32_e32 v124, 0xbfb8aa3b, v118
	v_mul_f32_e32 v125, 0xbfb8aa3b, v119
	v_exp_f32_e32 v124, v124
	v_exp_f32_e32 v125, v125
	s_nop 0
	v_pk_add_f32 v[124:125], v[124:125], 1.0 op_sel_hi:[1,0]
	v_rcp_f32_e32 v127, v167
	v_rcp_f32_e32 v126, v166
	s_nop 0
	v_pk_mul_f32 v[116:117], v[116:117], v[126:127]
	v_pk_mul_f32 v[114:115], v[114:115], v[160:161] op_sel_hi:[1,0]
	v_pk_mul_f32 v[112:113], v[112:113], v[116:117]
	v_rcp_f32_e32 v117, v125
	v_rcp_f32_e32 v116, v124
	s_nop 0
	v_pk_mul_f32 v[116:117], v[118:119], v[116:117]
	v_cvt_pk_bf16_f32 v118, v112, v113
	v_pk_mul_f32 v[114:115], v[114:115], v[116:117]
	v_mov_b64_e32 v[112:113], s[48:49]
	v_cvt_pk_bf16_f32 v116, v120, v121
	v_cvt_pk_bf16_f32 v119, v114, v115
	v_mad_i64_i32 v[120:121], s[0:1], v144, s44, v[112:113]
	v_lshlrev_b64 v[114:115], 1, v[152:153]
	v_cvt_pk_bf16_f32 v117, v122, v123
	v_lshl_add_u64 v[120:121], v[120:121], 0, v[114:115]
	global_store_dwordx4 v[120:121], v[116:119], off
	s_nop 1
	v_or_b32_e32 v116, 16, v144
	v_ashrrev_i32_e32 v117, 31, v116
	v_lshl_add_u64 v[118:119], v[116:117], 2, s[46:47]
	global_load_dword v117, v[118:119], off
	s_waitcnt vmcnt(0)
	v_fmamk_f32 v117, v117, 0x3a800000, v158
	v_mul_f32_e32 v118, 0x4b800000, v117
	v_cmp_gt_f32_e32 vcc, s43, v117
	s_nop 1
	v_cndmask_b32_e32 v117, v117, v118, vcc
	v_rsq_f32_e32 v117, v117
	s_nop 0
	v_mul_f32_e32 v118, 0x45800000, v117
	v_cndmask_b32_e32 v118, v117, v118, vcc
	v_pk_mul_f32 v[108:109], v[108:109], v[118:119] op_sel_hi:[1,0]
	v_pk_mul_f32 v[110:111], v[110:111], v[118:119] op_sel_hi:[1,0]
	v_mul_f32_e32 v117, 0xbfb8aa3b, v108
	v_mul_f32_e32 v119, 0xbfb8aa3b, v109
	v_exp_f32_e32 v120, v117
	v_exp_f32_e32 v121, v119
	v_mul_f32_e32 v122, 0xbfb8aa3b, v110
	v_mul_f32_e32 v123, 0xbfb8aa3b, v111
	v_exp_f32_e32 v122, v122
	v_pk_add_f32 v[120:121], v[120:121], 1.0 op_sel_hi:[1,0]
	v_exp_f32_e32 v123, v123
	s_nop 0
	v_pk_add_f32 v[122:123], v[122:123], 1.0 op_sel_hi:[1,0]
	v_pk_mul_f32 v[104:105], v[104:105], v[118:119] op_sel_hi:[1,0]
	v_pk_mul_f32 v[106:107], v[106:107], v[118:119] op_sel_hi:[1,0]
	v_rcp_f32_e32 v121, v121
	v_rcp_f32_e32 v120, v120
	s_nop 0
	v_pk_mul_f32 v[108:109], v[108:109], v[120:121]
	v_pk_mul_f32 v[104:105], v[104:105], v[108:109]
	v_rcp_f32_e32 v109, v123
	v_pk_mul_f32 v[100:101], v[100:101], v[118:119] op_sel_hi:[1,0]
	v_mul_f32_e32 v117, 0xbfb8aa3b, v100
	v_exp_f32_e32 v120, v117
	v_mul_f32_e32 v117, 0xbfb8aa3b, v101
	v_exp_f32_e32 v121, v117
	v_rcp_f32_e32 v108, v122
	s_nop 0
	v_pk_mul_f32 v[108:109], v[110:111], v[108:109]
	v_pk_add_f32 v[120:121], v[120:121], 1.0 op_sel_hi:[1,0]
	v_pk_mul_f32 v[106:107], v[106:107], v[108:109]
	s_nop 0
	v_pk_mul_f32 v[96:97], v[96:97], v[118:119] op_sel_hi:[1,0]
	v_rcp_f32_e32 v109, v121
	v_pk_mul_f32 v[102:103], v[102:103], v[118:119] op_sel_hi:[1,0]
	v_mul_f32_e32 v110, 0xbfb8aa3b, v102
	v_mul_f32_e32 v111, 0xbfb8aa3b, v103
	v_exp_f32_e32 v110, v110
	v_exp_f32_e32 v111, v111
	v_rcp_f32_e32 v108, v120
	s_nop 0
	v_pk_mul_f32 v[100:101], v[100:101], v[108:109]
	v_pk_add_f32 v[110:111], v[110:111], 1.0 op_sel_hi:[1,0]
	v_pk_mul_f32 v[100:101], v[96:97], v[100:101]
	s_nop 0
	v_pk_mul_f32 v[96:97], v[98:99], v[118:119] op_sel_hi:[1,0]
	v_rcp_f32_e32 v99, v111
	v_rcp_f32_e32 v98, v110
	s_nop 0
	v_pk_mul_f32 v[98:99], v[102:103], v[98:99]
	s_nop 0
	v_pk_mul_f32 v[102:103], v[96:97], v[98:99]
	v_cvt_pk_bf16_f32 v98, v100, v101
	v_mad_i64_i32 v[100:101], s[0:1], v116, s44, v[112:113]
	v_cvt_pk_bf16_f32 v96, v104, v105
	v_cvt_pk_bf16_f32 v97, v106, v107
	v_cvt_pk_bf16_f32 v99, v102, v103
	v_lshl_add_u64 v[100:101], v[100:101], 0, v[114:115]
	global_store_dwordx4 v[100:101], v[96:99], off
	s_nop 1
	v_or_b32_e32 v96, 32, v144
	v_ashrrev_i32_e32 v97, 31, v96
	v_lshl_add_u64 v[98:99], v[96:97], 2, s[46:47]
	global_load_dword v97, v[98:99], off
	s_waitcnt vmcnt(0)
; DI unsigned pk2(float lo, float hi) { f32x2_t v = {lo, hi}; bf16x2_t b = __builtin_convertvector(v, bf16x2_t); return __builtin_bit_cast(unsigned, b); }
; DI float sigmoidf_(float x) { return 1.0f / (1.0f + __expf(-x)); }
;     DI void operator()(AccRef acc, const Unit& u, int wr, int wc, int fr, int fq) const {
;     ...
;                 const int row = row0 + ai * HALF + m * 16; const float rs = rsqrtf(SS1[row] * (1.0f / DM) + EPSN);
;                 float h[8];
; #pragma unroll
;                 for (int n = 0; n < 2; ++n)
; #pragma unroll
;                     for (int e = 0; e < 4; ++e) { const float g = acc[ai][0][m][n][e] * rs, up = acc[ai][1][m][n][e] * rs; h[4 * n + e] = g * sigmoidf_(g) * up; }
;                 u32x4 w; w.x = pk2(h[0], h[1]); w.y = pk2(h[2], h[3]); w.z = pk2(h[4], h[5]); w.w = pk2(h[6], h[7]);
;                 *(u32x4*)(H + (size_t)row * DFF + col0) = w;
	v_fmamk_f32 v97, v97, 0x3a800000, v158
	v_mul_f32_e32 v98, 0x4b800000, v97
	v_cmp_gt_f32_e32 vcc, s43, v97
	s_nop 1
	v_cndmask_b32_e32 v97, v97, v98, vcc
	v_rsq_f32_e32 v97, v97
	s_nop 0
	v_mul_f32_e32 v98, 0x45800000, v97
	v_cndmask_b32_e32 v98, v97, v98, vcc
	v_pk_mul_f32 v[92:93], v[92:93], v[98:99] op_sel_hi:[1,0]
	s_nop 0
	v_mul_f32_e32 v97, 0xbfb8aa3b, v92
	v_exp_f32_e32 v100, v97
	v_mul_f32_e32 v97, 0xbfb8aa3b, v93
	v_exp_f32_e32 v101, v97
	s_nop 0
	v_pk_add_f32 v[100:101], v[100:101], 1.0 op_sel_hi:[1,0]
	s_nop 0
	s_nop 0
	v_pk_mul_f32 v[88:89], v[88:89], v[98:99] op_sel_hi:[1,0]
	v_rcp_f32_e32 v101, v101
	v_pk_mul_f32 v[94:95], v[94:95], v[98:99] op_sel_hi:[1,0]
	v_mul_f32_e32 v102, 0xbfb8aa3b, v94
	v_mul_f32_e32 v103, 0xbfb8aa3b, v95
	v_exp_f32_e32 v102, v102
	v_exp_f32_e32 v103, v103
	v_rcp_f32_e32 v100, v100
	s_nop 0
	v_pk_mul_f32 v[92:93], v[92:93], v[100:101]
	v_pk_add_f32 v[102:103], v[102:103], 1.0 op_sel_hi:[1,0]
	v_pk_mul_f32 v[88:89], v[88:89], v[92:93]
	s_nop 0
	v_pk_mul_f32 v[90:91], v[90:91], v[98:99] op_sel_hi:[1,0]
	v_rcp_f32_e32 v93, v103
	v_pk_mul_f32 v[84:85], v[84:85], v[98:99] op_sel_hi:[1,0]
	v_mul_f32_e32 v97, 0xbfb8aa3b, v84
	v_exp_f32_e32 v100, v97
	v_mul_f32_e32 v97, 0xbfb8aa3b, v85
	v_exp_f32_e32 v101, v97
	v_rcp_f32_e32 v92, v102
	s_nop 0
	v_pk_mul_f32 v[92:93], v[94:95], v[92:93]
	v_pk_add_f32 v[100:101], v[100:101], 1.0 op_sel_hi:[1,0]
	v_pk_mul_f32 v[90:91], v[90:91], v[92:93]
	s_nop 0
	v_pk_mul_f32 v[80:81], v[80:81], v[98:99] op_sel_hi:[1,0]
	v_rcp_f32_e32 v93, v101
	v_pk_mul_f32 v[86:87], v[86:87], v[98:99] op_sel_hi:[1,0]
	v_mul_f32_e32 v94, 0xbfb8aa3b, v86
	v_mul_f32_e32 v95, 0xbfb8aa3b, v87
	v_exp_f32_e32 v94, v94
	v_exp_f32_e32 v95, v95
	v_rcp_f32_e32 v92, v100
	s_nop 0
	v_pk_mul_f32 v[84:85], v[84:85], v[92:93]
	v_pk_add_f32 v[94:95], v[94:95], 1.0 op_sel_hi:[1,0]
	v_pk_mul_f32 v[84:85], v[80:81], v[84:85]
	s_nop 0
	v_pk_mul_f32 v[80:81], v[82:83], v[98:99] op_sel_hi:[1,0]
	v_rcp_f32_e32 v83, v95
	v_rcp_f32_e32 v82, v94
	s_nop 0
	v_pk_mul_f32 v[82:83], v[86:87], v[82:83]
	s_nop 0
	v_pk_mul_f32 v[86:87], v[80:81], v[82:83]
	v_cvt_pk_bf16_f32 v82, v84, v85
	v_mad_i64_i32 v[84:85], s[0:1], v96, s44, v[112:113]
	v_cvt_pk_bf16_f32 v80, v88, v89
	v_cvt_pk_bf16_f32 v81, v90, v91
	v_cvt_pk_bf16_f32 v83, v86, v87
	v_lshl_add_u64 v[84:85], v[84:85], 0, v[114:115]
	global_store_dwordx4 v[84:85], v[80:83], off
	s_nop 1
	v_or_b32_e32 v80, 48, v144
	v_ashrrev_i32_e32 v81, 31, v80
	v_lshl_add_u64 v[82:83], v[80:81], 2, s[46:47]
	global_load_dword v81, v[82:83], off
	s_waitcnt vmcnt(0)
	v_fmamk_f32 v81, v81, 0x3a800000, v158
	v_mul_f32_e32 v82, 0x4b800000, v81
	v_cmp_gt_f32_e32 vcc, s43, v81
	s_nop 1
	v_cndmask_b32_e32 v81, v81, v82, vcc
	v_rsq_f32_e32 v81, v81
	s_nop 0
	v_mul_f32_e32 v82, 0x45800000, v81
	v_cndmask_b32_e32 v82, v81, v82, vcc
	v_pk_mul_f32 v[76:77], v[76:77], v[82:83] op_sel_hi:[1,0]
	s_nop 0
	v_mul_f32_e32 v81, 0xbfb8aa3b, v76
	v_exp_f32_e32 v84, v81
	v_mul_f32_e32 v81, 0xbfb8aa3b, v77
	v_exp_f32_e32 v85, v81
	s_nop 0
	v_pk_add_f32 v[84:85], v[84:85], 1.0 op_sel_hi:[1,0]
	s_nop 0
	s_nop 0
	v_pk_mul_f32 v[72:73], v[72:73], v[82:83] op_sel_hi:[1,0]
	v_rcp_f32_e32 v85, v85
	v_pk_mul_f32 v[78:79], v[78:79], v[82:83] op_sel_hi:[1,0]
	v_mul_f32_e32 v86, 0xbfb8aa3b, v78
	v_mul_f32_e32 v87, 0xbfb8aa3b, v79
	v_exp_f32_e32 v86, v86
	v_exp_f32_e32 v87, v87
	v_rcp_f32_e32 v84, v84
	s_nop 0
	v_pk_mul_f32 v[76:77], v[76:77], v[84:85]
	v_pk_add_f32 v[86:87], v[86:87], 1.0 op_sel_hi:[1,0]
	v_pk_mul_f32 v[72:73], v[72:73], v[76:77]
	s_nop 0
	v_pk_mul_f32 v[74:75], v[74:75], v[82:83] op_sel_hi:[1,0]
	v_rcp_f32_e32 v77, v87
	v_pk_mul_f32 v[68:69], v[68:69], v[82:83] op_sel_hi:[1,0]
	v_mul_f32_e32 v81, 0xbfb8aa3b, v68
	v_exp_f32_e32 v84, v81
	v_mul_f32_e32 v81, 0xbfb8aa3b, v69
	v_exp_f32_e32 v85, v81
	v_rcp_f32_e32 v76, v86
	s_nop 0
	v_pk_mul_f32 v[76:77], v[78:79], v[76:77]
	v_pk_add_f32 v[84:85], v[84:85], 1.0 op_sel_hi:[1,0]
	v_pk_mul_f32 v[74:75], v[74:75], v[76:77]
	s_nop 0
	v_pk_mul_f32 v[64:65], v[64:65], v[82:83] op_sel_hi:[1,0]
	v_rcp_f32_e32 v77, v85
	v_pk_mul_f32 v[70:71], v[70:71], v[82:83] op_sel_hi:[1,0]
	v_mul_f32_e32 v78, 0xbfb8aa3b, v70
	v_mul_f32_e32 v79, 0xbfb8aa3b, v71
	v_exp_f32_e32 v78, v78
	v_exp_f32_e32 v79, v79
	v_rcp_f32_e32 v76, v84
	s_nop 0
	v_pk_mul_f32 v[68:69], v[68:69], v[76:77]
	v_pk_add_f32 v[78:79], v[78:79], 1.0 op_sel_hi:[1,0]
	v_pk_mul_f32 v[68:69], v[64:65], v[68:69]
	s_nop 0
	v_pk_mul_f32 v[64:65], v[66:67], v[82:83] op_sel_hi:[1,0]
	v_rcp_f32_e32 v67, v79
	v_rcp_f32_e32 v66, v78
	s_nop 0
	v_pk_mul_f32 v[66:67], v[70:71], v[66:67]
	s_nop 0
	v_pk_mul_f32 v[70:71], v[64:65], v[66:67]
	v_cvt_pk_bf16_f32 v66, v68, v69
	v_mad_i64_i32 v[68:69], s[0:1], v80, s44, v[112:113]
	v_cvt_pk_bf16_f32 v64, v72, v73
	v_cvt_pk_bf16_f32 v65, v74, v75
	v_cvt_pk_bf16_f32 v67, v70, v71
	v_lshl_add_u64 v[68:69], v[68:69], 0, v[114:115]
	global_store_dwordx4 v[68:69], v[64:67], off
	global_load_dword v64, v[146:147], off offset:512
	v_add_u32_e32 v70, 0x80, v144
	s_waitcnt vmcnt(0)
; DI unsigned pk2(float lo, float hi) { f32x2_t v = {lo, hi}; bf16x2_t b = __builtin_convertvector(v, bf16x2_t); return __builtin_bit_cast(unsigned, b); }
; DI float sigmoidf_(float x) { return 1.0f / (1.0f + __expf(-x)); }
;     DI void operator()(AccRef acc, const Unit& u, int wr, int wc, int fr, int fq) const {
;     ...
;                 const int row = row0 + ai * HALF + m * 16; const float rs = rsqrtf(SS1[row] * (1.0f / DM) + EPSN);
;                 float h[8];
; #pragma unroll
;                 for (int n = 0; n < 2; ++n)
; #pragma unroll
;                     for (int e = 0; e < 4; ++e) { const float g = acc[ai][0][m][n][e] * rs, up = acc[ai][1][m][n][e] * rs; h[4 * n + e] = g * sigmoidf_(g) * up; }
;                 u32x4 w; w.x = pk2(h[0], h[1]); w.y = pk2(h[2], h[3]); w.z = pk2(h[4], h[5]); w.w = pk2(h[6], h[7]);
;                 *(u32x4*)(H + (size_t)row * DFF + col0) = w;
	v_fmamk_f32 v64, v64, 0x3a800000, v158
	v_mul_f32_e32 v65, 0x4b800000, v64
	v_cmp_gt_f32_e32 vcc, s43, v64
	s_nop 1
	v_cndmask_b32_e32 v64, v64, v65, vcc
	v_rsq_f32_e32 v64, v64
	s_nop 0
	v_mul_f32_e32 v65, 0x45800000, v64
	v_cndmask_b32_e32 v64, v64, v65, vcc
	v_pk_mul_f32 v[60:61], v[60:61], v[64:65] op_sel_hi:[1,0]
	s_nop 0
	v_mul_f32_e32 v65, 0xbfb8aa3b, v60
	v_exp_f32_e32 v66, v65
	v_mul_f32_e32 v65, 0xbfb8aa3b, v61
	v_exp_f32_e32 v67, v65
	s_nop 0
	v_pk_add_f32 v[66:67], v[66:67], 1.0 op_sel_hi:[1,0]
	s_nop 0
	v_pk_mul_f32 v[56:57], v[56:57], v[64:65] op_sel_hi:[1,0]
	v_rcp_f32_e32 v67, v67
	v_pk_mul_f32 v[62:63], v[62:63], v[64:65] op_sel_hi:[1,0]
	v_mul_f32_e32 v68, 0xbfb8aa3b, v62
	v_mul_f32_e32 v69, 0xbfb8aa3b, v63
	v_exp_f32_e32 v68, v68
	v_exp_f32_e32 v69, v69
	v_rcp_f32_e32 v66, v66
	s_nop 0
	v_pk_mul_f32 v[60:61], v[60:61], v[66:67]
	v_pk_add_f32 v[68:69], v[68:69], 1.0 op_sel_hi:[1,0]
	s_nop 0
	v_pk_mul_f32 v[56:57], v[56:57], v[60:61]
	v_pk_mul_f32 v[58:59], v[58:59], v[64:65] op_sel_hi:[1,0]
	v_rcp_f32_e32 v61, v69
	v_pk_mul_f32 v[52:53], v[52:53], v[64:65] op_sel_hi:[1,0]
	v_mul_f32_e32 v65, 0xbfb8aa3b, v52
	v_exp_f32_e32 v66, v65
	v_mul_f32_e32 v65, 0xbfb8aa3b, v53
	v_exp_f32_e32 v67, v65
	v_rcp_f32_e32 v60, v68
	s_nop 0
	v_pk_mul_f32 v[60:61], v[62:63], v[60:61]
	v_pk_add_f32 v[66:67], v[66:67], 1.0 op_sel_hi:[1,0]
	v_pk_mul_f32 v[58:59], v[58:59], v[60:61]
	v_pk_mul_f32 v[48:49], v[48:49], v[64:65] op_sel_hi:[1,0]
	v_rcp_f32_e32 v61, v67
	v_pk_mul_f32 v[54:55], v[54:55], v[64:65] op_sel_hi:[1,0]
	v_mul_f32_e32 v62, 0xbfb8aa3b, v54
	v_mul_f32_e32 v63, 0xbfb8aa3b, v55
	v_exp_f32_e32 v62, v62
	v_exp_f32_e32 v63, v63
	v_rcp_f32_e32 v60, v66
	s_nop 0
	v_pk_mul_f32 v[52:53], v[52:53], v[60:61]
	v_pk_add_f32 v[62:63], v[62:63], 1.0 op_sel_hi:[1,0]
	v_pk_mul_f32 v[52:53], v[48:49], v[52:53]
	v_pk_mul_f32 v[48:49], v[50:51], v[64:65] op_sel_hi:[1,0]
	v_rcp_f32_e32 v51, v63
	v_rcp_f32_e32 v50, v62
	s_nop 0
	v_pk_mul_f32 v[50:51], v[54:55], v[50:51]
	s_nop 0
	v_pk_mul_f32 v[54:55], v[48:49], v[50:51]
	v_cvt_pk_bf16_f32 v50, v52, v53
	v_mad_i64_i32 v[52:53], s[0:1], v70, s44, v[112:113]
	v_cvt_pk_bf16_f32 v48, v56, v57
	v_cvt_pk_bf16_f32 v49, v58, v59
	v_cvt_pk_bf16_f32 v51, v54, v55
	v_lshl_add_u64 v[52:53], v[52:53], 0, v[114:115]
	global_store_dwordx4 v[52:53], v[48:51], off
	global_load_dword v48, v[146:147], off offset:576
	v_add_u32_e32 v54, 0x90, v144
	s_waitcnt vmcnt(0)
	v_fmamk_f32 v48, v48, 0x3a800000, v158
	v_mul_f32_e32 v49, 0x4b800000, v48
	v_cmp_gt_f32_e32 vcc, s43, v48
	s_nop 1
	v_cndmask_b32_e32 v48, v48, v49, vcc
	v_rsq_f32_e32 v48, v48
	s_nop 0
	v_mul_f32_e32 v49, 0x45800000, v48
	v_cndmask_b32_e32 v48, v48, v49, vcc
	v_pk_mul_f32 v[44:45], v[44:45], v[48:49] op_sel_hi:[1,0]
	s_nop 0
	v_mul_f32_e32 v49, 0xbfb8aa3b, v44
	v_exp_f32_e32 v50, v49
	v_mul_f32_e32 v49, 0xbfb8aa3b, v45
	v_exp_f32_e32 v51, v49
	s_nop 0
	v_pk_add_f32 v[50:51], v[50:51], 1.0 op_sel_hi:[1,0]
	s_nop 0
	v_pk_mul_f32 v[40:41], v[40:41], v[48:49] op_sel_hi:[1,0]
	v_rcp_f32_e32 v51, v51
	v_pk_mul_f32 v[46:47], v[46:47], v[48:49] op_sel_hi:[1,0]
	v_mul_f32_e32 v52, 0xbfb8aa3b, v46
	v_mul_f32_e32 v53, 0xbfb8aa3b, v47
	v_exp_f32_e32 v52, v52
	v_exp_f32_e32 v53, v53
	v_rcp_f32_e32 v50, v50
	s_nop 0
	v_pk_mul_f32 v[44:45], v[44:45], v[50:51]
	v_pk_add_f32 v[52:53], v[52:53], 1.0 op_sel_hi:[1,0]
	s_nop 0
	v_pk_mul_f32 v[40:41], v[40:41], v[44:45]
	v_pk_mul_f32 v[42:43], v[42:43], v[48:49] op_sel_hi:[1,0]
	v_rcp_f32_e32 v45, v53
	v_pk_mul_f32 v[36:37], v[36:37], v[48:49] op_sel_hi:[1,0]
	v_mul_f32_e32 v49, 0xbfb8aa3b, v36
	v_exp_f32_e32 v50, v49
	v_mul_f32_e32 v49, 0xbfb8aa3b, v37
	v_exp_f32_e32 v51, v49
	v_rcp_f32_e32 v44, v52
	s_nop 0
	v_pk_mul_f32 v[44:45], v[46:47], v[44:45]
	v_pk_add_f32 v[50:51], v[50:51], 1.0 op_sel_hi:[1,0]
	v_pk_mul_f32 v[42:43], v[42:43], v[44:45]
	v_pk_mul_f32 v[32:33], v[32:33], v[48:49] op_sel_hi:[1,0]
	v_rcp_f32_e32 v45, v51
	v_pk_mul_f32 v[38:39], v[38:39], v[48:49] op_sel_hi:[1,0]
	v_mul_f32_e32 v46, 0xbfb8aa3b, v38
	v_mul_f32_e32 v47, 0xbfb8aa3b, v39
	v_exp_f32_e32 v46, v46
	v_exp_f32_e32 v47, v47
	v_rcp_f32_e32 v44, v50
	s_nop 0
	v_pk_mul_f32 v[36:37], v[36:37], v[44:45]
	v_pk_add_f32 v[46:47], v[46:47], 1.0 op_sel_hi:[1,0]
	v_pk_mul_f32 v[36:37], v[32:33], v[36:37]
	v_pk_mul_f32 v[32:33], v[34:35], v[48:49] op_sel_hi:[1,0]
	v_rcp_f32_e32 v35, v47
	v_rcp_f32_e32 v34, v46
	s_nop 0
	v_pk_mul_f32 v[34:35], v[38:39], v[34:35]
	s_nop 0
	v_pk_mul_f32 v[38:39], v[32:33], v[34:35]
	v_cvt_pk_bf16_f32 v34, v36, v37
	v_mad_i64_i32 v[36:37], s[0:1], v54, s44, v[112:113]
	v_cvt_pk_bf16_f32 v32, v40, v41
	v_cvt_pk_bf16_f32 v33, v42, v43
	v_cvt_pk_bf16_f32 v35, v38, v39
	v_lshl_add_u64 v[36:37], v[36:37], 0, v[114:115]
	global_store_dwordx4 v[36:37], v[32:35], off
	global_load_dword v32, v[146:147], off offset:640
	v_add_u32_e32 v38, 0xa0, v144
	s_waitcnt vmcnt(0)
; DI unsigned pk2(float lo, float hi) { f32x2_t v = {lo, hi}; bf16x2_t b = __builtin_convertvector(v, bf16x2_t); return __builtin_bit_cast(unsigned, b); }
; DI float sigmoidf_(float x) { return 1.0f / (1.0f + __expf(-x)); }
;     DI void operator()(AccRef acc, const Unit& u, int wr, int wc, int fr, int fq) const {
;     ...
;                 const int row = row0 + ai * HALF + m * 16; const float rs = rsqrtf(SS1[row] * (1.0f / DM) + EPSN);
;                 float h[8];
; #pragma unroll
;                 for (int n = 0; n < 2; ++n)
; #pragma unroll
;                     for (int e = 0; e < 4; ++e) { const float g = acc[ai][0][m][n][e] * rs, up = acc[ai][1][m][n][e] * rs; h[4 * n + e] = g * sigmoidf_(g) * up; }
;                 u32x4 w; w.x = pk2(h[0], h[1]); w.y = pk2(h[2], h[3]); w.z = pk2(h[4], h[5]); w.w = pk2(h[6], h[7]);
;                 *(u32x4*)(H + (size_t)row * DFF + col0) = w;
	v_fmamk_f32 v32, v32, 0x3a800000, v158
	v_mul_f32_e32 v33, 0x4b800000, v32
	v_cmp_gt_f32_e32 vcc, s43, v32
	s_nop 1
	v_cndmask_b32_e32 v32, v32, v33, vcc
	v_rsq_f32_e32 v32, v32
	s_nop 0
	v_mul_f32_e32 v33, 0x45800000, v32
	v_cndmask_b32_e32 v32, v32, v33, vcc
	v_pk_mul_f32 v[28:29], v[28:29], v[32:33] op_sel_hi:[1,0]
	s_nop 0
	v_mul_f32_e32 v33, 0xbfb8aa3b, v28
	v_exp_f32_e32 v34, v33
	v_mul_f32_e32 v33, 0xbfb8aa3b, v29
	v_exp_f32_e32 v35, v33
	s_nop 0
	v_pk_add_f32 v[34:35], v[34:35], 1.0 op_sel_hi:[1,0]
	s_nop 0
	v_pk_mul_f32 v[24:25], v[24:25], v[32:33] op_sel_hi:[1,0]
	v_rcp_f32_e32 v35, v35
	v_pk_mul_f32 v[30:31], v[30:31], v[32:33] op_sel_hi:[1,0]
	v_mul_f32_e32 v36, 0xbfb8aa3b, v30
	v_mul_f32_e32 v37, 0xbfb8aa3b, v31
	v_exp_f32_e32 v36, v36
	v_exp_f32_e32 v37, v37
	v_rcp_f32_e32 v34, v34
	s_nop 0
	v_pk_mul_f32 v[28:29], v[28:29], v[34:35]
	v_pk_add_f32 v[36:37], v[36:37], 1.0 op_sel_hi:[1,0]
	s_nop 0
	v_pk_mul_f32 v[24:25], v[24:25], v[28:29]
	v_pk_mul_f32 v[26:27], v[26:27], v[32:33] op_sel_hi:[1,0]
	v_rcp_f32_e32 v29, v37
	v_pk_mul_f32 v[20:21], v[20:21], v[32:33] op_sel_hi:[1,0]
	v_mul_f32_e32 v33, 0xbfb8aa3b, v20
	v_exp_f32_e32 v34, v33
	v_mul_f32_e32 v33, 0xbfb8aa3b, v21
	v_exp_f32_e32 v35, v33
	v_rcp_f32_e32 v28, v36
	s_nop 0
	v_pk_mul_f32 v[28:29], v[30:31], v[28:29]
	v_pk_add_f32 v[34:35], v[34:35], 1.0 op_sel_hi:[1,0]
	v_pk_mul_f32 v[26:27], v[26:27], v[28:29]
	v_pk_mul_f32 v[16:17], v[16:17], v[32:33] op_sel_hi:[1,0]
	v_rcp_f32_e32 v29, v35
	v_pk_mul_f32 v[22:23], v[22:23], v[32:33] op_sel_hi:[1,0]
	v_mul_f32_e32 v30, 0xbfb8aa3b, v22
	v_mul_f32_e32 v31, 0xbfb8aa3b, v23
	v_exp_f32_e32 v30, v30
	v_exp_f32_e32 v31, v31
	v_rcp_f32_e32 v28, v34
	s_nop 0
	v_pk_mul_f32 v[20:21], v[20:21], v[28:29]
	v_pk_add_f32 v[30:31], v[30:31], 1.0 op_sel_hi:[1,0]
	v_pk_mul_f32 v[20:21], v[16:17], v[20:21]
	v_pk_mul_f32 v[16:17], v[18:19], v[32:33] op_sel_hi:[1,0]
	v_rcp_f32_e32 v19, v31
	v_rcp_f32_e32 v18, v30
	s_nop 0
	v_pk_mul_f32 v[18:19], v[22:23], v[18:19]
	s_nop 0
	v_pk_mul_f32 v[22:23], v[16:17], v[18:19]
	v_cvt_pk_bf16_f32 v18, v20, v21
	v_mad_i64_i32 v[20:21], s[0:1], v38, s44, v[112:113]
	v_cvt_pk_bf16_f32 v16, v24, v25
	v_cvt_pk_bf16_f32 v17, v26, v27
	v_cvt_pk_bf16_f32 v19, v22, v23
	v_lshl_add_u64 v[20:21], v[20:21], 0, v[114:115]
	global_store_dwordx4 v[20:21], v[16:19], off
	global_load_dword v16, v[146:147], off offset:704
	v_add_u32_e32 v22, 0xb0, v144
	s_waitcnt vmcnt(0)
	v_fmamk_f32 v16, v16, 0x3a800000, v158
	v_mul_f32_e32 v17, 0x4b800000, v16
	v_cmp_gt_f32_e32 vcc, s43, v16
	s_nop 1
	v_cndmask_b32_e32 v16, v16, v17, vcc
	v_rsq_f32_e32 v16, v16
	s_nop 0
	v_mul_f32_e32 v17, 0x45800000, v16
	v_cndmask_b32_e32 v16, v16, v17, vcc
	v_pk_mul_f32 v[12:13], v[12:13], v[16:17] op_sel_hi:[1,0]
	s_nop 0
	v_mul_f32_e32 v17, 0xbfb8aa3b, v12
	v_exp_f32_e32 v18, v17
	v_mul_f32_e32 v17, 0xbfb8aa3b, v13
	v_exp_f32_e32 v19, v17
	s_nop 0
	v_pk_add_f32 v[18:19], v[18:19], 1.0 op_sel_hi:[1,0]
	s_nop 0
	v_pk_mul_f32 v[8:9], v[8:9], v[16:17] op_sel_hi:[1,0]
	v_rcp_f32_e32 v19, v19
	v_pk_mul_f32 v[14:15], v[14:15], v[16:17] op_sel_hi:[1,0]
	v_mul_f32_e32 v20, 0xbfb8aa3b, v14
	v_mul_f32_e32 v21, 0xbfb8aa3b, v15
	v_exp_f32_e32 v20, v20
	v_exp_f32_e32 v21, v21
	v_rcp_f32_e32 v18, v18
	s_nop 0
	v_pk_mul_f32 v[12:13], v[12:13], v[18:19]
	v_pk_add_f32 v[20:21], v[20:21], 1.0 op_sel_hi:[1,0]
	s_nop 0
	v_pk_mul_f32 v[8:9], v[8:9], v[12:13]
	v_pk_mul_f32 v[10:11], v[10:11], v[16:17] op_sel_hi:[1,0]
	v_rcp_f32_e32 v13, v21
	v_pk_mul_f32 v[4:5], v[4:5], v[16:17] op_sel_hi:[1,0]
	v_mul_f32_e32 v17, 0xbfb8aa3b, v4
	v_exp_f32_e32 v18, v17
	v_mul_f32_e32 v17, 0xbfb8aa3b, v5
	v_exp_f32_e32 v19, v17
	v_rcp_f32_e32 v12, v20
	s_nop 0
	v_pk_mul_f32 v[12:13], v[14:15], v[12:13]
	v_pk_add_f32 v[18:19], v[18:19], 1.0 op_sel_hi:[1,0]
	v_pk_mul_f32 v[10:11], v[10:11], v[12:13]
	v_pk_mul_f32 v[0:1], v[0:1], v[16:17] op_sel_hi:[1,0]
	v_rcp_f32_e32 v13, v19
	v_pk_mul_f32 v[6:7], v[6:7], v[16:17] op_sel_hi:[1,0]
	v_mul_f32_e32 v14, 0xbfb8aa3b, v6
	v_mul_f32_e32 v15, 0xbfb8aa3b, v7
	v_exp_f32_e32 v14, v14
	v_exp_f32_e32 v15, v15
	v_rcp_f32_e32 v12, v18
	s_nop 0
	v_pk_mul_f32 v[4:5], v[4:5], v[12:13]
	v_pk_add_f32 v[14:15], v[14:15], 1.0 op_sel_hi:[1,0]
	v_pk_mul_f32 v[4:5], v[0:1], v[4:5]
	v_pk_mul_f32 v[0:1], v[2:3], v[16:17] op_sel_hi:[1,0]
	v_rcp_f32_e32 v3, v15
	v_rcp_f32_e32 v2, v14
	s_nop 0
	v_pk_mul_f32 v[2:3], v[6:7], v[2:3]
	s_andn2_b64 vcc, exec, s[2:3]
	v_pk_mul_f32 v[6:7], v[0:1], v[2:3]
	v_cvt_pk_bf16_f32 v2, v4, v5
	v_mad_i64_i32 v[4:5], s[0:1], v22, s44, v[112:113]
	v_cvt_pk_bf16_f32 v0, v8, v9
	v_cvt_pk_bf16_f32 v1, v10, v11
	v_cvt_pk_bf16_f32 v3, v6, v7
	v_lshl_add_u64 v[4:5], v[4:5], 0, v[114:115]
	s_mov_b64 s[0:1], -1
	global_store_dwordx4 v[4:5], v[0:3], off
	s_cbranch_vccnz .LBB0_1483
	s_andn2_b64 vcc, exec, s[14:15]
	s_cbranch_vccnz .LBB0_1482
	s_barrier
	s_branch .LBB0_1482

; DI unsigned pk2(float lo, float hi) { f32x2_t v = {lo, hi}; bf16x2_t b = __builtin_convertvector(v, bf16x2_t); return __builtin_bit_cast(unsigned, b); }
; DI float sigmoidf_(float x) { return 1.0f / (1.0f + __expf(-x)); }
;     DI void operator()(AccRef acc, const Unit& u, int wr, int wc, int fr, int fq) const {
;     ...
;                 const int row = row0 + ai * HALF + m * 16; const float rs = rsqrtf(SS1[row] * (1.0f / DM) + EPSN);
;                 float h[8];
; #pragma unroll
;                 for (int n = 0; n < 2; ++n)
; #pragma unroll
;                     for (int e = 0; e < 4; ++e) { const float g = acc[ai][0][m][n][e] * rs, up = acc[ai][1][m][n][e] * rs; h[4 * n + e] = g * sigmoidf_(g) * up; }
;                 u32x4 w; w.x = pk2(h[0], h[1]); w.y = pk2(h[2], h[3]); w.z = pk2(h[4], h[5]); w.w = pk2(h[6], h[7]);
;                 *(u32x4*)(H + (size_t)row * DFF + col0) = w;
.LBB0_1669:
	v_lshl_add_u32 v144, s0, 8, v149
	v_ashrrev_i32_e32 v145, 31, v144
	v_lshl_add_u64 v[146:147], v[144:145], 2, s[18:19]
	global_load_dword v145, v[146:147], off
	s_waitcnt vmcnt(0)
	v_fmamk_f32 v145, v145, 0x3a800000, v158
	v_mul_f32_e32 v152, 0x4b800000, v145
	v_cmp_gt_f32_e32 vcc, s51, v145
	s_nop 1
	v_cndmask_b32_e32 v145, v145, v152, vcc
	v_rsq_f32_e32 v145, v145
	v_lshl_or_b32 v152, s1, 7, v154
	v_ashrrev_i32_e32 v153, 31, v152
	v_mul_f32_e32 v159, 0x45800000, v145
	v_cndmask_b32_e32 v160, v145, v159, vcc
	v_pk_mul_f32 v[124:125], v[124:125], v[160:161] op_sel_hi:[1,0]
	v_pk_mul_f32 v[126:127], v[126:127], v[160:161] op_sel_hi:[1,0]
	v_mul_f32_e32 v145, 0xbfb8aa3b, v124
	v_mul_f32_e32 v159, 0xbfb8aa3b, v125
	v_exp_f32_e32 v162, v145
	v_exp_f32_e32 v163, v159
	v_pk_mul_f32 v[120:121], v[120:121], v[160:161] op_sel_hi:[1,0]
	v_pk_mul_f32 v[122:123], v[122:123], v[160:161] op_sel_hi:[1,0]
	v_pk_mul_f32 v[116:117], v[116:117], v[160:161] op_sel_hi:[1,0]
	v_mul_f32_e32 v161, 0xbfb8aa3b, v126
	v_mul_f32_e32 v165, 0xbfb8aa3b, v127
	v_exp_f32_e32 v164, v161
	v_exp_f32_e32 v165, v165
	v_pk_add_f32 v[162:163], v[162:163], 1.0 op_sel_hi:[1,0]
	v_pk_mul_f32 v[112:113], v[112:113], v[160:161] op_sel_hi:[1,0]
	v_pk_add_f32 v[164:165], v[164:165], 1.0 op_sel_hi:[1,0]
	v_mul_f32_e32 v166, 0xbfb8aa3b, v116
	v_mul_f32_e32 v167, 0xbfb8aa3b, v117
	v_exp_f32_e32 v166, v166
	v_exp_f32_e32 v167, v167
	s_nop 0
	v_pk_add_f32 v[166:167], v[166:167], 1.0 op_sel_hi:[1,0]
	v_rcp_f32_e32 v163, v163
	v_rcp_f32_e32 v162, v162
	s_nop 0
	v_pk_mul_f32 v[124:125], v[124:125], v[162:163]
	v_rcp_f32_e32 v163, v165
	v_rcp_f32_e32 v162, v164
	v_pk_mul_f32 v[120:121], v[120:121], v[124:125]
	v_pk_mul_f32 v[124:125], v[126:127], v[162:163]
	v_pk_mul_f32 v[118:119], v[118:119], v[160:161] op_sel_hi:[1,0]
	v_pk_mul_f32 v[122:123], v[122:123], v[124:125]
	v_mul_f32_e32 v124, 0xbfb8aa3b, v118
	v_mul_f32_e32 v125, 0xbfb8aa3b, v119
	v_exp_f32_e32 v124, v124
	v_exp_f32_e32 v125, v125
	s_nop 0
	v_pk_add_f32 v[124:125], v[124:125], 1.0 op_sel_hi:[1,0]
	v_rcp_f32_e32 v127, v167
	v_rcp_f32_e32 v126, v166
	s_nop 0
	v_pk_mul_f32 v[116:117], v[116:117], v[126:127]
	v_pk_mul_f32 v[114:115], v[114:115], v[160:161] op_sel_hi:[1,0]
	v_pk_mul_f32 v[112:113], v[112:113], v[116:117]
	v_rcp_f32_e32 v117, v125
	v_rcp_f32_e32 v116, v124
	s_nop 0
	v_pk_mul_f32 v[116:117], v[118:119], v[116:117]
	v_cvt_pk_bf16_f32 v118, v112, v113
	v_pk_mul_f32 v[114:115], v[114:115], v[116:117]
	v_mov_b64_e32 v[112:113], s[48:49]
	v_cvt_pk_bf16_f32 v116, v120, v121
	v_cvt_pk_bf16_f32 v119, v114, v115
	v_mad_i64_i32 v[120:121], s[0:1], v144, s52, v[112:113]
	v_lshlrev_b64 v[114:115], 1, v[152:153]
	v_cvt_pk_bf16_f32 v117, v122, v123
	v_lshl_add_u64 v[120:121], v[120:121], 0, v[114:115]
	global_store_dwordx4 v[120:121], v[116:119], off
	s_nop 1
	v_or_b32_e32 v116, 16, v144
	v_ashrrev_i32_e32 v117, 31, v116
	v_lshl_add_u64 v[118:119], v[116:117], 2, s[18:19]
	global_load_dword v117, v[118:119], off
	s_waitcnt vmcnt(0)
	v_fmamk_f32 v117, v117, 0x3a800000, v158
	v_mul_f32_e32 v118, 0x4b800000, v117
	v_cmp_gt_f32_e32 vcc, s51, v117
	s_nop 1
	v_cndmask_b32_e32 v117, v117, v118, vcc
	v_rsq_f32_e32 v117, v117
	s_nop 0
	v_mul_f32_e32 v118, 0x45800000, v117
	v_cndmask_b32_e32 v118, v117, v118, vcc
	v_pk_mul_f32 v[108:109], v[108:109], v[118:119] op_sel_hi:[1,0]
	v_pk_mul_f32 v[110:111], v[110:111], v[118:119] op_sel_hi:[1,0]
	v_mul_f32_e32 v117, 0xbfb8aa3b, v108
	v_mul_f32_e32 v119, 0xbfb8aa3b, v109
	v_exp_f32_e32 v120, v117
	v_exp_f32_e32 v121, v119
	v_mul_f32_e32 v122, 0xbfb8aa3b, v110
	v_mul_f32_e32 v123, 0xbfb8aa3b, v111
	v_exp_f32_e32 v122, v122
	v_pk_add_f32 v[120:121], v[120:121], 1.0 op_sel_hi:[1,0]
	v_exp_f32_e32 v123, v123
	s_nop 0
	v_pk_add_f32 v[122:123], v[122:123], 1.0 op_sel_hi:[1,0]
	v_pk_mul_f32 v[104:105], v[104:105], v[118:119] op_sel_hi:[1,0]
	v_pk_mul_f32 v[106:107], v[106:107], v[118:119] op_sel_hi:[1,0]
	v_rcp_f32_e32 v121, v121
	v_rcp_f32_e32 v120, v120
	s_nop 0
	v_pk_mul_f32 v[108:109], v[108:109], v[120:121]
	v_pk_mul_f32 v[104:105], v[104:105], v[108:109]
	v_rcp_f32_e32 v109, v123
	v_pk_mul_f32 v[100:101], v[100:101], v[118:119] op_sel_hi:[1,0]
	v_mul_f32_e32 v117, 0xbfb8aa3b, v100
	v_exp_f32_e32 v120, v117
	v_mul_f32_e32 v117, 0xbfb8aa3b, v101
	v_exp_f32_e32 v121, v117
	v_rcp_f32_e32 v108, v122
	s_nop 0
	v_pk_mul_f32 v[108:109], v[110:111], v[108:109]
	v_pk_add_f32 v[120:121], v[120:121], 1.0 op_sel_hi:[1,0]
	v_pk_mul_f32 v[106:107], v[106:107], v[108:109]
	s_nop 0
	v_pk_mul_f32 v[96:97], v[96:97], v[118:119] op_sel_hi:[1,0]
	v_rcp_f32_e32 v109, v121
	v_pk_mul_f32 v[102:103], v[102:103], v[118:119] op_sel_hi:[1,0]
	v_mul_f32_e32 v110, 0xbfb8aa3b, v102
	v_mul_f32_e32 v111, 0xbfb8aa3b, v103
	v_exp_f32_e32 v110, v110
	v_exp_f32_e32 v111, v111
	v_rcp_f32_e32 v108, v120
	s_nop 0
	v_pk_mul_f32 v[100:101], v[100:101], v[108:109]
	v_pk_add_f32 v[110:111], v[110:111], 1.0 op_sel_hi:[1,0]
	v_pk_mul_f32 v[100:101], v[96:97], v[100:101]
	s_nop 0
	v_pk_mul_f32 v[96:97], v[98:99], v[118:119] op_sel_hi:[1,0]
	v_rcp_f32_e32 v99, v111
	v_rcp_f32_e32 v98, v110
	s_nop 0
	v_pk_mul_f32 v[98:99], v[102:103], v[98:99]
	s_nop 0
	v_pk_mul_f32 v[102:103], v[96:97], v[98:99]
	v_cvt_pk_bf16_f32 v98, v100, v101
	v_mad_i64_i32 v[100:101], s[0:1], v116, s52, v[112:113]
	v_cvt_pk_bf16_f32 v96, v104, v105
	v_cvt_pk_bf16_f32 v97, v106, v107
	v_cvt_pk_bf16_f32 v99, v102, v103
	v_lshl_add_u64 v[100:101], v[100:101], 0, v[114:115]
	global_store_dwordx4 v[100:101], v[96:99], off
	s_nop 1
	v_or_b32_e32 v96, 32, v144
	v_ashrrev_i32_e32 v97, 31, v96
	v_lshl_add_u64 v[98:99], v[96:97], 2, s[18:19]
	global_load_dword v97, v[98:99], off
	s_waitcnt vmcnt(0)
; DI unsigned pk2(float lo, float hi) { f32x2_t v = {lo, hi}; bf16x2_t b = __builtin_convertvector(v, bf16x2_t); return __builtin_bit_cast(unsigned, b); }
; DI float sigmoidf_(float x) { return 1.0f / (1.0f + __expf(-x)); }
;     DI void operator()(AccRef acc, const Unit& u, int wr, int wc, int fr, int fq) const {
;     ...
;                 const int row = row0 + ai * HALF + m * 16; const float rs = rsqrtf(SS1[row] * (1.0f / DM) + EPSN);
;                 float h[8];
; #pragma unroll
;                 for (int n = 0; n < 2; ++n)
; #pragma unroll
;                     for (int e = 0; e < 4; ++e) { const float g = acc[ai][0][m][n][e] * rs, up = acc[ai][1][m][n][e] * rs; h[4 * n + e] = g * sigmoidf_(g) * up; }
;                 u32x4 w; w.x = pk2(h[0], h[1]); w.y = pk2(h[2], h[3]); w.z = pk2(h[4], h[5]); w.w = pk2(h[6], h[7]);
;                 *(u32x4*)(H + (size_t)row * DFF + col0) = w;
	v_fmamk_f32 v97, v97, 0x3a800000, v158
	v_mul_f32_e32 v98, 0x4b800000, v97
	v_cmp_gt_f32_e32 vcc, s51, v97
	s_nop 1
	v_cndmask_b32_e32 v97, v97, v98, vcc
	v_rsq_f32_e32 v97, v97
	s_nop 0
	v_mul_f32_e32 v98, 0x45800000, v97
	v_cndmask_b32_e32 v98, v97, v98, vcc
	v_pk_mul_f32 v[92:93], v[92:93], v[98:99] op_sel_hi:[1,0]
	s_nop 0
	v_mul_f32_e32 v97, 0xbfb8aa3b, v92
	v_exp_f32_e32 v100, v97
	v_mul_f32_e32 v97, 0xbfb8aa3b, v93
	v_exp_f32_e32 v101, v97
	s_nop 0
	v_pk_add_f32 v[100:101], v[100:101], 1.0 op_sel_hi:[1,0]
	s_nop 0
	s_nop 0
	v_pk_mul_f32 v[88:89], v[88:89], v[98:99] op_sel_hi:[1,0]
	v_rcp_f32_e32 v101, v101
	v_pk_mul_f32 v[94:95], v[94:95], v[98:99] op_sel_hi:[1,0]
	v_mul_f32_e32 v102, 0xbfb8aa3b, v94
	v_mul_f32_e32 v103, 0xbfb8aa3b, v95
	v_exp_f32_e32 v102, v102
	v_exp_f32_e32 v103, v103
	v_rcp_f32_e32 v100, v100
	s_nop 0
	v_pk_mul_f32 v[92:93], v[92:93], v[100:101]
	v_pk_add_f32 v[102:103], v[102:103], 1.0 op_sel_hi:[1,0]
	v_pk_mul_f32 v[88:89], v[88:89], v[92:93]
	s_nop 0
	v_pk_mul_f32 v[90:91], v[90:91], v[98:99] op_sel_hi:[1,0]
	v_rcp_f32_e32 v93, v103
	v_pk_mul_f32 v[84:85], v[84:85], v[98:99] op_sel_hi:[1,0]
	v_mul_f32_e32 v97, 0xbfb8aa3b, v84
	v_exp_f32_e32 v100, v97
	v_mul_f32_e32 v97, 0xbfb8aa3b, v85
	v_exp_f32_e32 v101, v97
	v_rcp_f32_e32 v92, v102
	s_nop 0
	v_pk_mul_f32 v[92:93], v[94:95], v[92:93]
	v_pk_add_f32 v[100:101], v[100:101], 1.0 op_sel_hi:[1,0]
	v_pk_mul_f32 v[90:91], v[90:91], v[92:93]
	s_nop 0
	v_pk_mul_f32 v[80:81], v[80:81], v[98:99] op_sel_hi:[1,0]
	v_rcp_f32_e32 v93, v101
	v_pk_mul_f32 v[86:87], v[86:87], v[98:99] op_sel_hi:[1,0]
	v_mul_f32_e32 v94, 0xbfb8aa3b, v86
	v_mul_f32_e32 v95, 0xbfb8aa3b, v87
	v_exp_f32_e32 v94, v94
	v_exp_f32_e32 v95, v95
	v_rcp_f32_e32 v92, v100
	s_nop 0
	v_pk_mul_f32 v[84:85], v[84:85], v[92:93]
	v_pk_add_f32 v[94:95], v[94:95], 1.0 op_sel_hi:[1,0]
	v_pk_mul_f32 v[84:85], v[80:81], v[84:85]
	s_nop 0
	v_pk_mul_f32 v[80:81], v[82:83], v[98:99] op_sel_hi:[1,0]
	v_rcp_f32_e32 v83, v95
	v_rcp_f32_e32 v82, v94
	s_nop 0
	v_pk_mul_f32 v[82:83], v[86:87], v[82:83]
	s_nop 0
	v_pk_mul_f32 v[86:87], v[80:81], v[82:83]
	v_cvt_pk_bf16_f32 v82, v84, v85
	v_mad_i64_i32 v[84:85], s[0:1], v96, s52, v[112:113]
	v_cvt_pk_bf16_f32 v80, v88, v89
	v_cvt_pk_bf16_f32 v81, v90, v91
	v_cvt_pk_bf16_f32 v83, v86, v87
	v_lshl_add_u64 v[84:85], v[84:85], 0, v[114:115]
	global_store_dwordx4 v[84:85], v[80:83], off
	s_nop 1
	v_or_b32_e32 v80, 48, v144
	v_ashrrev_i32_e32 v81, 31, v80
	v_lshl_add_u64 v[82:83], v[80:81], 2, s[18:19]
	global_load_dword v81, v[82:83], off
	s_waitcnt vmcnt(0)
	v_fmamk_f32 v81, v81, 0x3a800000, v158
	v_mul_f32_e32 v82, 0x4b800000, v81
	v_cmp_gt_f32_e32 vcc, s51, v81
	s_nop 1
	v_cndmask_b32_e32 v81, v81, v82, vcc
	v_rsq_f32_e32 v81, v81
	s_nop 0
	v_mul_f32_e32 v82, 0x45800000, v81
	v_cndmask_b32_e32 v82, v81, v82, vcc
	v_pk_mul_f32 v[76:77], v[76:77], v[82:83] op_sel_hi:[1,0]
	s_nop 0
	v_mul_f32_e32 v81, 0xbfb8aa3b, v76
	v_exp_f32_e32 v84, v81
	v_mul_f32_e32 v81, 0xbfb8aa3b, v77
	v_exp_f32_e32 v85, v81
	s_nop 0
	v_pk_add_f32 v[84:85], v[84:85], 1.0 op_sel_hi:[1,0]
	s_nop 0
	s_nop 0
	v_pk_mul_f32 v[72:73], v[72:73], v[82:83] op_sel_hi:[1,0]
	v_rcp_f32_e32 v85, v85
	v_pk_mul_f32 v[78:79], v[78:79], v[82:83] op_sel_hi:[1,0]
	v_mul_f32_e32 v86, 0xbfb8aa3b, v78
	v_mul_f32_e32 v87, 0xbfb8aa3b, v79
	v_exp_f32_e32 v86, v86
	v_exp_f32_e32 v87, v87
	v_rcp_f32_e32 v84, v84
	s_nop 0
	v_pk_mul_f32 v[76:77], v[76:77], v[84:85]
	v_pk_add_f32 v[86:87], v[86:87], 1.0 op_sel_hi:[1,0]
	v_pk_mul_f32 v[72:73], v[72:73], v[76:77]
	s_nop 0
	v_pk_mul_f32 v[74:75], v[74:75], v[82:83] op_sel_hi:[1,0]
	v_rcp_f32_e32 v77, v87
	v_pk_mul_f32 v[68:69], v[68:69], v[82:83] op_sel_hi:[1,0]
	v_mul_f32_e32 v81, 0xbfb8aa3b, v68
	v_exp_f32_e32 v84, v81
	v_mul_f32_e32 v81, 0xbfb8aa3b, v69
	v_exp_f32_e32 v85, v81
	v_rcp_f32_e32 v76, v86
	s_nop 0
	v_pk_mul_f32 v[76:77], v[78:79], v[76:77]
	v_pk_add_f32 v[84:85], v[84:85], 1.0 op_sel_hi:[1,0]
	v_pk_mul_f32 v[74:75], v[74:75], v[76:77]
	s_nop 0
	v_pk_mul_f32 v[64:65], v[64:65], v[82:83] op_sel_hi:[1,0]
	v_rcp_f32_e32 v77, v85
	v_pk_mul_f32 v[70:71], v[70:71], v[82:83] op_sel_hi:[1,0]
	v_mul_f32_e32 v78, 0xbfb8aa3b, v70
	v_mul_f32_e32 v79, 0xbfb8aa3b, v71
	v_exp_f32_e32 v78, v78
	v_exp_f32_e32 v79, v79
	v_rcp_f32_e32 v76, v84
	s_nop 0
	v_pk_mul_f32 v[68:69], v[68:69], v[76:77]
	v_pk_add_f32 v[78:79], v[78:79], 1.0 op_sel_hi:[1,0]
	v_pk_mul_f32 v[68:69], v[64:65], v[68:69]
	s_nop 0
	v_pk_mul_f32 v[64:65], v[66:67], v[82:83] op_sel_hi:[1,0]
	v_rcp_f32_e32 v67, v79
	v_rcp_f32_e32 v66, v78
	s_nop 0
	v_pk_mul_f32 v[66:67], v[70:71], v[66:67]
	s_nop 0
	v_pk_mul_f32 v[70:71], v[64:65], v[66:67]
	v_cvt_pk_bf16_f32 v66, v68, v69
	v_mad_i64_i32 v[68:69], s[0:1], v80, s52, v[112:113]
	v_cvt_pk_bf16_f32 v64, v72, v73
	v_cvt_pk_bf16_f32 v65, v74, v75
	v_cvt_pk_bf16_f32 v67, v70, v71
	v_lshl_add_u64 v[68:69], v[68:69], 0, v[114:115]
	global_store_dwordx4 v[68:69], v[64:67], off
	global_load_dword v64, v[146:147], off offset:512
	v_add_u32_e32 v70, 0x80, v144
	s_waitcnt vmcnt(0)
; DI unsigned pk2(float lo, float hi) { f32x2_t v = {lo, hi}; bf16x2_t b = __builtin_convertvector(v, bf16x2_t); return __builtin_bit_cast(unsigned, b); }
; DI float sigmoidf_(float x) { return 1.0f / (1.0f + __expf(-x)); }
;     DI void operator()(AccRef acc, const Unit& u, int wr, int wc, int fr, int fq) const {
;     ...
;                 const int row = row0 + ai * HALF + m * 16; const float rs = rsqrtf(SS1[row] * (1.0f / DM) + EPSN);
;                 float h[8];
; #pragma unroll
;                 for (int n = 0; n < 2; ++n)
; #pragma unroll
;                     for (int e = 0; e < 4; ++e) { const float g = acc[ai][0][m][n][e] * rs, up = acc[ai][1][m][n][e] * rs; h[4 * n + e] = g * sigmoidf_(g) * up; }
;                 u32x4 w; w.x = pk2(h[0], h[1]); w.y = pk2(h[2], h[3]); w.z = pk2(h[4], h[5]); w.w = pk2(h[6], h[7]);
;                 *(u32x4*)(H + (size_t)row * DFF + col0) = w;
	v_fmamk_f32 v64, v64, 0x3a800000, v158
	v_mul_f32_e32 v65, 0x4b800000, v64
	v_cmp_gt_f32_e32 vcc, s51, v64
	s_nop 1
	v_cndmask_b32_e32 v64, v64, v65, vcc
	v_rsq_f32_e32 v64, v64
	s_nop 0
	v_mul_f32_e32 v65, 0x45800000, v64
	v_cndmask_b32_e32 v64, v64, v65, vcc
	v_pk_mul_f32 v[60:61], v[60:61], v[64:65] op_sel_hi:[1,0]
	s_nop 0
	v_mul_f32_e32 v65, 0xbfb8aa3b, v60
	v_exp_f32_e32 v66, v65
	v_mul_f32_e32 v65, 0xbfb8aa3b, v61
	v_exp_f32_e32 v67, v65
	s_nop 0
	v_pk_add_f32 v[66:67], v[66:67], 1.0 op_sel_hi:[1,0]
	s_nop 0
	v_pk_mul_f32 v[56:57], v[56:57], v[64:65] op_sel_hi:[1,0]
	v_rcp_f32_e32 v67, v67
	v_pk_mul_f32 v[62:63], v[62:63], v[64:65] op_sel_hi:[1,0]
	v_mul_f32_e32 v68, 0xbfb8aa3b, v62
	v_mul_f32_e32 v69, 0xbfb8aa3b, v63
	v_exp_f32_e32 v68, v68
	v_exp_f32_e32 v69, v69
	v_rcp_f32_e32 v66, v66
	s_nop 0
	v_pk_mul_f32 v[60:61], v[60:61], v[66:67]
	v_pk_add_f32 v[68:69], v[68:69], 1.0 op_sel_hi:[1,0]
	s_nop 0
	v_pk_mul_f32 v[56:57], v[56:57], v[60:61]
	v_pk_mul_f32 v[58:59], v[58:59], v[64:65] op_sel_hi:[1,0]
	v_rcp_f32_e32 v61, v69
	v_pk_mul_f32 v[52:53], v[52:53], v[64:65] op_sel_hi:[1,0]
	v_mul_f32_e32 v65, 0xbfb8aa3b, v52
	v_exp_f32_e32 v66, v65
	v_mul_f32_e32 v65, 0xbfb8aa3b, v53
	v_exp_f32_e32 v67, v65
	v_rcp_f32_e32 v60, v68
	s_nop 0
	v_pk_mul_f32 v[60:61], v[62:63], v[60:61]
	v_pk_add_f32 v[66:67], v[66:67], 1.0 op_sel_hi:[1,0]
	v_pk_mul_f32 v[58:59], v[58:59], v[60:61]
	v_pk_mul_f32 v[48:49], v[48:49], v[64:65] op_sel_hi:[1,0]
	v_rcp_f32_e32 v61, v67
	v_pk_mul_f32 v[54:55], v[54:55], v[64:65] op_sel_hi:[1,0]
	v_mul_f32_e32 v62, 0xbfb8aa3b, v54
	v_mul_f32_e32 v63, 0xbfb8aa3b, v55
	v_exp_f32_e32 v62, v62
	v_exp_f32_e32 v63, v63
	v_rcp_f32_e32 v60, v66
	s_nop 0
	v_pk_mul_f32 v[52:53], v[52:53], v[60:61]
	v_pk_add_f32 v[62:63], v[62:63], 1.0 op_sel_hi:[1,0]
	v_pk_mul_f32 v[52:53], v[48:49], v[52:53]
	v_pk_mul_f32 v[48:49], v[50:51], v[64:65] op_sel_hi:[1,0]
	v_rcp_f32_e32 v51, v63
	v_rcp_f32_e32 v50, v62
	s_nop 0
	v_pk_mul_f32 v[50:51], v[54:55], v[50:51]
	s_nop 0
	v_pk_mul_f32 v[54:55], v[48:49], v[50:51]
	v_cvt_pk_bf16_f32 v50, v52, v53
	v_mad_i64_i32 v[52:53], s[0:1], v70, s52, v[112:113]
	v_cvt_pk_bf16_f32 v48, v56, v57
	v_cvt_pk_bf16_f32 v49, v58, v59
	v_cvt_pk_bf16_f32 v51, v54, v55
	v_lshl_add_u64 v[52:53], v[52:53], 0, v[114:115]
	global_store_dwordx4 v[52:53], v[48:51], off
	global_load_dword v48, v[146:147], off offset:576
	v_add_u32_e32 v54, 0x90, v144
	s_waitcnt vmcnt(0)
	v_fmamk_f32 v48, v48, 0x3a800000, v158
	v_mul_f32_e32 v49, 0x4b800000, v48
	v_cmp_gt_f32_e32 vcc, s51, v48
	s_nop 1
	v_cndmask_b32_e32 v48, v48, v49, vcc
	v_rsq_f32_e32 v48, v48
	s_nop 0
	v_mul_f32_e32 v49, 0x45800000, v48
	v_cndmask_b32_e32 v48, v48, v49, vcc
	v_pk_mul_f32 v[44:45], v[44:45], v[48:49] op_sel_hi:[1,0]
	s_nop 0
	v_mul_f32_e32 v49, 0xbfb8aa3b, v44
	v_exp_f32_e32 v50, v49
	v_mul_f32_e32 v49, 0xbfb8aa3b, v45
	v_exp_f32_e32 v51, v49
	s_nop 0
	v_pk_add_f32 v[50:51], v[50:51], 1.0 op_sel_hi:[1,0]
	s_nop 0
	v_pk_mul_f32 v[40:41], v[40:41], v[48:49] op_sel_hi:[1,0]
	v_rcp_f32_e32 v51, v51
	v_pk_mul_f32 v[46:47], v[46:47], v[48:49] op_sel_hi:[1,0]
	v_mul_f32_e32 v52, 0xbfb8aa3b, v46
	v_mul_f32_e32 v53, 0xbfb8aa3b, v47
	v_exp_f32_e32 v52, v52
	v_exp_f32_e32 v53, v53
	v_rcp_f32_e32 v50, v50
	s_nop 0
	v_pk_mul_f32 v[44:45], v[44:45], v[50:51]
	v_pk_add_f32 v[52:53], v[52:53], 1.0 op_sel_hi:[1,0]
	s_nop 0
	v_pk_mul_f32 v[40:41], v[40:41], v[44:45]
	v_pk_mul_f32 v[42:43], v[42:43], v[48:49] op_sel_hi:[1,0]
	v_rcp_f32_e32 v45, v53
	v_pk_mul_f32 v[36:37], v[36:37], v[48:49] op_sel_hi:[1,0]
	v_mul_f32_e32 v49, 0xbfb8aa3b, v36
	v_exp_f32_e32 v50, v49
	v_mul_f32_e32 v49, 0xbfb8aa3b, v37
	v_exp_f32_e32 v51, v49
	v_rcp_f32_e32 v44, v52
	s_nop 0
	v_pk_mul_f32 v[44:45], v[46:47], v[44:45]
	v_pk_add_f32 v[50:51], v[50:51], 1.0 op_sel_hi:[1,0]
	v_pk_mul_f32 v[42:43], v[42:43], v[44:45]
	v_pk_mul_f32 v[32:33], v[32:33], v[48:49] op_sel_hi:[1,0]
	v_rcp_f32_e32 v45, v51
	v_pk_mul_f32 v[38:39], v[38:39], v[48:49] op_sel_hi:[1,0]
	v_mul_f32_e32 v46, 0xbfb8aa3b, v38
	v_mul_f32_e32 v47, 0xbfb8aa3b, v39
	v_exp_f32_e32 v46, v46
	v_exp_f32_e32 v47, v47
	v_rcp_f32_e32 v44, v50
	s_nop 0
	v_pk_mul_f32 v[36:37], v[36:37], v[44:45]
	v_pk_add_f32 v[46:47], v[46:47], 1.0 op_sel_hi:[1,0]
	v_pk_mul_f32 v[36:37], v[32:33], v[36:37]
	v_pk_mul_f32 v[32:33], v[34:35], v[48:49] op_sel_hi:[1,0]
	v_rcp_f32_e32 v35, v47
	v_rcp_f32_e32 v34, v46
	s_nop 0
	v_pk_mul_f32 v[34:35], v[38:39], v[34:35]
	s_nop 0
	v_pk_mul_f32 v[38:39], v[32:33], v[34:35]
	v_cvt_pk_bf16_f32 v34, v36, v37
	v_mad_i64_i32 v[36:37], s[0:1], v54, s52, v[112:113]
	v_cvt_pk_bf16_f32 v32, v40, v41
	v_cvt_pk_bf16_f32 v33, v42, v43
	v_cvt_pk_bf16_f32 v35, v38, v39
	v_lshl_add_u64 v[36:37], v[36:37], 0, v[114:115]
	global_store_dwordx4 v[36:37], v[32:35], off
	global_load_dword v32, v[146:147], off offset:640
	v_add_u32_e32 v38, 0xa0, v144
	s_waitcnt vmcnt(0)
; DI unsigned pk2(float lo, float hi) { f32x2_t v = {lo, hi}; bf16x2_t b = __builtin_convertvector(v, bf16x2_t); return __builtin_bit_cast(unsigned, b); }
; DI float sigmoidf_(float x) { return 1.0f / (1.0f + __expf(-x)); }
;     DI void operator()(AccRef acc, const Unit& u, int wr, int wc, int fr, int fq) const {
;     ...
;                 const int row = row0 + ai * HALF + m * 16; const float rs = rsqrtf(SS1[row] * (1.0f / DM) + EPSN);
;                 float h[8];
; #pragma unroll
;                 for (int n = 0; n < 2; ++n)
; #pragma unroll
;                     for (int e = 0; e < 4; ++e) { const float g = acc[ai][0][m][n][e] * rs, up = acc[ai][1][m][n][e] * rs; h[4 * n + e] = g * sigmoidf_(g) * up; }
;                 u32x4 w; w.x = pk2(h[0], h[1]); w.y = pk2(h[2], h[3]); w.z = pk2(h[4], h[5]); w.w = pk2(h[6], h[7]);
;                 *(u32x4*)(H + (size_t)row * DFF + col0) = w;
	v_fmamk_f32 v32, v32, 0x3a800000, v158
	v_mul_f32_e32 v33, 0x4b800000, v32
	v_cmp_gt_f32_e32 vcc, s51, v32
	s_nop 1
	v_cndmask_b32_e32 v32, v32, v33, vcc
	v_rsq_f32_e32 v32, v32
	s_nop 0
	v_mul_f32_e32 v33, 0x45800000, v32
	v_cndmask_b32_e32 v32, v32, v33, vcc
	v_pk_mul_f32 v[28:29], v[28:29], v[32:33] op_sel_hi:[1,0]
	s_nop 0
	v_mul_f32_e32 v33, 0xbfb8aa3b, v28
	v_exp_f32_e32 v34, v33
	v_mul_f32_e32 v33, 0xbfb8aa3b, v29
	v_exp_f32_e32 v35, v33
	s_nop 0
	v_pk_add_f32 v[34:35], v[34:35], 1.0 op_sel_hi:[1,0]
	s_nop 0
	v_pk_mul_f32 v[24:25], v[24:25], v[32:33] op_sel_hi:[1,0]
	v_rcp_f32_e32 v35, v35
	v_pk_mul_f32 v[30:31], v[30:31], v[32:33] op_sel_hi:[1,0]
	v_mul_f32_e32 v36, 0xbfb8aa3b, v30
	v_mul_f32_e32 v37, 0xbfb8aa3b, v31
	v_exp_f32_e32 v36, v36
	v_exp_f32_e32 v37, v37
	v_rcp_f32_e32 v34, v34
	s_nop 0
	v_pk_mul_f32 v[28:29], v[28:29], v[34:35]
	v_pk_add_f32 v[36:37], v[36:37], 1.0 op_sel_hi:[1,0]
	s_nop 0
	v_pk_mul_f32 v[24:25], v[24:25], v[28:29]
	v_pk_mul_f32 v[26:27], v[26:27], v[32:33] op_sel_hi:[1,0]
	v_rcp_f32_e32 v29, v37
	v_pk_mul_f32 v[20:21], v[20:21], v[32:33] op_sel_hi:[1,0]
	v_mul_f32_e32 v33, 0xbfb8aa3b, v20
	v_exp_f32_e32 v34, v33
	v_mul_f32_e32 v33, 0xbfb8aa3b, v21
	v_exp_f32_e32 v35, v33
	v_rcp_f32_e32 v28, v36
	s_nop 0
	v_pk_mul_f32 v[28:29], v[30:31], v[28:29]
	v_pk_add_f32 v[34:35], v[34:35], 1.0 op_sel_hi:[1,0]
	v_pk_mul_f32 v[26:27], v[26:27], v[28:29]
	v_pk_mul_f32 v[16:17], v[16:17], v[32:33] op_sel_hi:[1,0]
	v_rcp_f32_e32 v29, v35
	v_pk_mul_f32 v[22:23], v[22:23], v[32:33] op_sel_hi:[1,0]
	v_mul_f32_e32 v30, 0xbfb8aa3b, v22
	v_mul_f32_e32 v31, 0xbfb8aa3b, v23
	v_exp_f32_e32 v30, v30
	v_exp_f32_e32 v31, v31
	v_rcp_f32_e32 v28, v34
	s_nop 0
	v_pk_mul_f32 v[20:21], v[20:21], v[28:29]
	v_pk_add_f32 v[30:31], v[30:31], 1.0 op_sel_hi:[1,0]
	v_pk_mul_f32 v[20:21], v[16:17], v[20:21]
	v_pk_mul_f32 v[16:17], v[18:19], v[32:33] op_sel_hi:[1,0]
	v_rcp_f32_e32 v19, v31
	v_rcp_f32_e32 v18, v30
	s_nop 0
	v_pk_mul_f32 v[18:19], v[22:23], v[18:19]
	s_nop 0
	v_pk_mul_f32 v[22:23], v[16:17], v[18:19]
	v_cvt_pk_bf16_f32 v18, v20, v21
	v_mad_i64_i32 v[20:21], s[0:1], v38, s52, v[112:113]
	v_cvt_pk_bf16_f32 v16, v24, v25
	v_cvt_pk_bf16_f32 v17, v26, v27
	v_cvt_pk_bf16_f32 v19, v22, v23
	v_lshl_add_u64 v[20:21], v[20:21], 0, v[114:115]
	global_store_dwordx4 v[20:21], v[16:19], off
	global_load_dword v16, v[146:147], off offset:704
	v_add_u32_e32 v22, 0xb0, v144
	s_waitcnt vmcnt(0)
	v_fmamk_f32 v16, v16, 0x3a800000, v158
	v_mul_f32_e32 v17, 0x4b800000, v16
	v_cmp_gt_f32_e32 vcc, s51, v16
	s_nop 1
	v_cndmask_b32_e32 v16, v16, v17, vcc
	v_rsq_f32_e32 v16, v16
	s_nop 0
	v_mul_f32_e32 v17, 0x45800000, v16
	v_cndmask_b32_e32 v16, v16, v17, vcc
	v_pk_mul_f32 v[12:13], v[12:13], v[16:17] op_sel_hi:[1,0]
	s_nop 0
	v_mul_f32_e32 v17, 0xbfb8aa3b, v12
	v_exp_f32_e32 v18, v17
	v_mul_f32_e32 v17, 0xbfb8aa3b, v13
	v_exp_f32_e32 v19, v17
	s_nop 0
	v_pk_add_f32 v[18:19], v[18:19], 1.0 op_sel_hi:[1,0]
	s_nop 0
	v_pk_mul_f32 v[8:9], v[8:9], v[16:17] op_sel_hi:[1,0]
	v_rcp_f32_e32 v19, v19
	v_pk_mul_f32 v[14:15], v[14:15], v[16:17] op_sel_hi:[1,0]
	v_mul_f32_e32 v20, 0xbfb8aa3b, v14
	v_mul_f32_e32 v21, 0xbfb8aa3b, v15
	v_exp_f32_e32 v20, v20
	v_exp_f32_e32 v21, v21
	v_rcp_f32_e32 v18, v18
	s_nop 0
	v_pk_mul_f32 v[12:13], v[12:13], v[18:19]
	v_pk_add_f32 v[20:21], v[20:21], 1.0 op_sel_hi:[1,0]
	s_nop 0
	v_pk_mul_f32 v[8:9], v[8:9], v[12:13]
	v_pk_mul_f32 v[10:11], v[10:11], v[16:17] op_sel_hi:[1,0]
	v_rcp_f32_e32 v13, v21
	v_pk_mul_f32 v[4:5], v[4:5], v[16:17] op_sel_hi:[1,0]
	v_mul_f32_e32 v17, 0xbfb8aa3b, v4
	v_exp_f32_e32 v18, v17
	v_mul_f32_e32 v17, 0xbfb8aa3b, v5
	v_exp_f32_e32 v19, v17
	v_rcp_f32_e32 v12, v20
	s_nop 0
	v_pk_mul_f32 v[12:13], v[14:15], v[12:13]
	v_pk_add_f32 v[18:19], v[18:19], 1.0 op_sel_hi:[1,0]
	v_pk_mul_f32 v[10:11], v[10:11], v[12:13]
	v_pk_mul_f32 v[0:1], v[0:1], v[16:17] op_sel_hi:[1,0]
	v_rcp_f32_e32 v13, v19
	v_pk_mul_f32 v[6:7], v[6:7], v[16:17] op_sel_hi:[1,0]
	v_mul_f32_e32 v14, 0xbfb8aa3b, v6
	v_mul_f32_e32 v15, 0xbfb8aa3b, v7
	v_exp_f32_e32 v14, v14
	v_exp_f32_e32 v15, v15
	v_rcp_f32_e32 v12, v18
	s_nop 0
	v_pk_mul_f32 v[4:5], v[4:5], v[12:13]
	v_pk_add_f32 v[14:15], v[14:15], 1.0 op_sel_hi:[1,0]
	v_pk_mul_f32 v[4:5], v[0:1], v[4:5]
	v_pk_mul_f32 v[0:1], v[2:3], v[16:17] op_sel_hi:[1,0]
	v_rcp_f32_e32 v3, v15
	v_rcp_f32_e32 v2, v14
	s_nop 0
	v_pk_mul_f32 v[2:3], v[6:7], v[2:3]
	s_andn2_b64 vcc, exec, s[2:3]
	v_pk_mul_f32 v[6:7], v[0:1], v[2:3]
	v_cvt_pk_bf16_f32 v2, v4, v5
	v_mad_i64_i32 v[4:5], s[0:1], v22, s52, v[112:113]
	v_cvt_pk_bf16_f32 v0, v8, v9
	v_cvt_pk_bf16_f32 v1, v10, v11
	v_cvt_pk_bf16_f32 v3, v6, v7
	v_lshl_add_u64 v[4:5], v[4:5], 0, v[114:115]
	s_mov_b64 s[0:1], -1
	global_store_dwordx4 v[4:5], v[0:3], off
	s_cbranch_vccnz .LBB0_1662
	s_andn2_b64 vcc, exec, s[16:17]
	s_cbranch_vccnz .LBB0_1661
	s_barrier
	s_branch .LBB0_1661
